# FFN-up epilogue: ssq block and conv weights prefetched into LDS by LDS-DMA at K-loop start (double-buffered), epilogue reads via ds_read; no vmcnt(0) before accumulator zeroing; store-ack waits betwee
# speedup vs baseline: 1.0194x; 1.0194x over previous
; #define LAS __attribute__((address_space(3)))
; #define PG8_BAR __builtin_amdgcn_s_barrier()
; __device__ __forceinline__ float u64f(u64 q) { return (float)(unsigned)(q >> 32) * 4294967296.f + (float)(unsigned)q; }
; template <class Epi, class Sched, bool APERM = false, bool HALFN = false>
; __device__ __forceinline__ void gemm_phase(LAS unsigned char* lds, const int tid_in, const int K, const Sched& S, const Epi& E) {
;     ...
; #pragma unroll
;         for (int a = 0; a < 2; ++a)
; #pragma unroll
;             for (int b = 0; b < 2; ++b)
; #pragma unroll
;                 for (int m = 0; m < 4; ++m)
; #pragma unroll
;                     for (int n = 0; n < 2; ++n) acc[a][b][m][n] = (f32x4){0.f, 0.f, 0.f, 0.f};
;         cur = nxt; cA = nA; cB = nB; ++ui;
;         if (wr == 1) PG8_BAR;
;     __device__ __forceinline__ void operator()(const f32x4 (&acc)[2][2][4][2], const CU2& u, int wr, int wc, int fr_, int fq_) const {
;     ...
;         { u64 q_[8];
; #pragma unroll
;           for (int j = 0; j < 8; ++j) q_[j] = ssq[(unsigned)(tb + j) < (unsigned)T_ ? tb + j : 0];
; #pragma unroll
;           for (int j = 0; j < 8; ++j) rsv[j] = (unsigned)(tb + j) < (unsigned)T_ ? rsqrtf(u64f(q_[j]) * SSQ_INV + EPS) : 0.f; }
;         if (wr == 0 && fr == 15) {
; #pragma unroll
;             for (int bj = 0; bj < 2; ++bj)
; #pragma unroll
;                 for (int n = 0; n < 2; ++n) { *(LAS f32x4*)(hal + 128 * bj + cl + 4 * n) = acc[1][bj][2][n] * rsv[6]; *(LAS f32x4*)(hal + 256 + 128 * bj + cl + 4 * n) = acc[1][bj][3][n] * rsv[7]; }
;         }
;         asm volatile("s_waitcnt lgkmcnt(0)" ::: "memory"); __builtin_amdgcn_s_barrier(); asm volatile("" ::: "memory");
; #pragma unroll
;         for (int n = 0; n < 2; ++n) {
;             const float* wp = cw + 128 * u.pn + cl + 4 * n; const float* bp = cb + 128 * u.pn + cl + 4 * n;
;             const f32x4 g0 = *(const f32x4*)wp, g1 = *(const f32x4*)(wp + 2 * FF_), g2 = *(const f32x4*)(wp + 4 * FF_), gb = *(const f32x4*)bp;
;             const f32x4 v0 = *(const f32x4*)(wp + FF_), v1 = *(const f32x4*)(wp + 3 * FF_), v2 = *(const f32x4*)(wp + 5 * FF_), vb = *(const f32x4*)(bp + FF_);
.LBB0_901:
	s_add_u32 s11, s4, 0x100
	v_mov_b32_e32 v44, 0
	s_addc_u32 s12, s5, 0
	s_mov_b32 s13, -2
	v_mov_b32_e32 v45, v44
	v_mov_b32_e32 v46, v44
	v_mov_b32_e32 v47, v44
	s_waitcnt lgkmcnt(0)
	v_mov_b32_e32 v76, v44
	v_mov_b32_e32 v77, v44
	v_mov_b32_e32 v78, v44
	v_mov_b32_e32 v79, v44
	v_mov_b32_e32 v54, v44
	v_mov_b32_e32 v55, v44
	v_mov_b32_e32 v56, v44
	v_mov_b32_e32 v57, v44
	v_mov_b32_e32 v84, v44
	v_mov_b32_e32 v85, v44
	v_mov_b32_e32 v86, v44
	v_mov_b32_e32 v87, v44
	v_mov_b32_e32 v0, v44
	v_mov_b32_e32 v1, v44
	v_mov_b32_e32 v2, v44
	v_mov_b32_e32 v3, v44
	v_mov_b32_e32 v88, v44
	v_mov_b32_e32 v89, v44
	v_mov_b32_e32 v90, v44
	v_mov_b32_e32 v91, v44
	v_mov_b32_e32 v8, v44
	v_mov_b32_e32 v9, v44
	v_mov_b32_e32 v10, v44
	v_mov_b32_e32 v11, v44
	v_mov_b32_e32 v96, v44
	v_mov_b32_e32 v97, v44
	v_mov_b32_e32 v98, v44
	v_mov_b32_e32 v99, v44
	v_mov_b32_e32 v68, v44
	v_mov_b32_e32 v69, v44
	v_mov_b32_e32 v70, v44
	v_mov_b32_e32 v71, v44
	v_mov_b32_e32 v80, v44
	v_mov_b32_e32 v81, v44
	v_mov_b32_e32 v82, v44
	v_mov_b32_e32 v83, v44
	v_mov_b32_e32 v72, v44
	v_mov_b32_e32 v73, v44
	v_mov_b32_e32 v74, v44
	v_mov_b32_e32 v75, v44
	v_mov_b32_e32 v48, v44
	v_mov_b32_e32 v49, v44
	v_mov_b32_e32 v50, v44
	v_mov_b32_e32 v51, v44
	v_mov_b32_e32 v4, v44
	v_mov_b32_e32 v5, v44
	v_mov_b32_e32 v6, v44
	v_mov_b32_e32 v7, v44
	v_mov_b32_e32 v92, v44
	v_mov_b32_e32 v93, v44
	v_mov_b32_e32 v94, v44
	v_mov_b32_e32 v95, v44
	v_mov_b32_e32 v12, v44
	v_mov_b32_e32 v13, v44
	v_mov_b32_e32 v14, v44
	v_mov_b32_e32 v15, v44
	v_mov_b32_e32 v100, v44
	v_mov_b32_e32 v101, v44
	v_mov_b32_e32 v102, v44
	v_mov_b32_e32 v103, v44
	v_mov_b32_e32 v16, v44
	v_mov_b32_e32 v17, v44
	v_mov_b32_e32 v18, v44
	v_mov_b32_e32 v19, v44
	v_mov_b32_e32 v104, v44
	v_mov_b32_e32 v105, v44
	v_mov_b32_e32 v106, v44
	v_mov_b32_e32 v107, v44
	v_mov_b32_e32 v24, v44
	v_mov_b32_e32 v25, v44
	v_mov_b32_e32 v26, v44
	v_mov_b32_e32 v27, v44
	s_waitcnt vmcnt(0)
	v_mov_b32_e32 v112, v44
	v_mov_b32_e32 v113, v44
	v_mov_b32_e32 v114, v44
	v_mov_b32_e32 v115, v44
	v_mov_b32_e32 v32, v44
	v_mov_b32_e32 v33, v44
	v_mov_b32_e32 v34, v44
	v_mov_b32_e32 v35, v44
	v_mov_b32_e32 v120, v44
	v_mov_b32_e32 v121, v44
	v_mov_b32_e32 v122, v44
	v_mov_b32_e32 v123, v44
	v_mov_b32_e32 v40, v44
	v_mov_b32_e32 v41, v44
	v_mov_b32_e32 v42, v44
	v_mov_b32_e32 v43, v44
	v_mov_b32_e32 v144, v44
	v_mov_b32_e32 v145, v44
	v_mov_b32_e32 v146, v44
	v_mov_b32_e32 v147, v44
	v_mov_b32_e32 v20, v44
	v_mov_b32_e32 v21, v44
	v_mov_b32_e32 v22, v44
	v_mov_b32_e32 v23, v44
	v_mov_b32_e32 v108, v44
	v_mov_b32_e32 v109, v44
	v_mov_b32_e32 v110, v44
	v_mov_b32_e32 v111, v44
	v_mov_b32_e32 v28, v44
	v_mov_b32_e32 v29, v44
	v_mov_b32_e32 v30, v44
	v_mov_b32_e32 v31, v44
	v_mov_b32_e32 v116, v44
	v_mov_b32_e32 v117, v44
	v_mov_b32_e32 v118, v44
	v_mov_b32_e32 v119, v44
	v_mov_b32_e32 v36, v44
	v_mov_b32_e32 v37, v44
	v_mov_b32_e32 v38, v44
	v_mov_b32_e32 v39, v44
	v_mov_b32_e32 v124, v44
	v_mov_b32_e32 v125, v44
	v_mov_b32_e32 v126, v44
	v_mov_b32_e32 v127, v44
	v_mov_b32_e32 v58, v44
	v_mov_b32_e32 v59, v44
	v_mov_b32_e32 v60, v44
	v_mov_b32_e32 v61, v44
	v_mov_b32_e32 v148, v44
	v_mov_b32_e32 v149, v44
	v_mov_b32_e32 v150, v44
	v_mov_b32_e32 v151, v44
	v_readfirstlane_b32 s26, v234
	s_and_b32 s27, s10, 1
	s_mulk_i32 s27, 0x1800
	s_lshr_b32 s26, s26, 6
	s_add_i32 s27, s27, 0x20800
	s_cmp_gt_u32 s26, 5
	s_cbranch_scc1 .Lpf_done
	s_cmp_gt_u32 s26, 3
	s_cbranch_scc1 .Lpf_ssq
	s_sub_u32 s28, s4, s95
	s_lshr_b32 s28, s28, 20
	s_lshl_b32 s28, s28, 9
	s_lshr_b32 s29, s26, 1
	s_mulk_i32 s29, 0x5800
	s_add_i32 s28, s28, s29
	s_bitcmp1_b32 s26, 0
	s_cselect_b32 s29, 0x16000, 0
	s_cselect_b32 s30, s74, s76
	s_cselect_b32 s31, s75, s77
	s_cselect_b32 s53, 0, 0xb000
	s_add_i32 s29, s29, s28
	s_add_i32 s53, s53, s28
	s_add_u32 s28, s76, s29
	s_addc_u32 s29, s77, 0
	s_add_u32 s30, s30, s53
	s_addc_u32 s31, s31, 0
	v_and_b32_e32 v236, 31, v235
	v_lshlrev_b32_e32 v236, 4, v236
	v_mov_b32_e32 v237, 0
	v_cmp_gt_u32_e32 vcc, 32, v235
	v_mov_b32_e32 v248, s30
	v_mov_b32_e32 v249, s31
	v_mov_b32_e32 v250, s28
	v_mov_b32_e32 v251, s29
	s_nop 0
	v_cndmask_b32_e32 v248, v248, v250, vcc
	v_cndmask_b32_e32 v249, v249, v251, vcc
	v_lshl_add_u64 v[236:237], v[248:249], 0, v[236:237]
	s_lshl_b32 s28, s26, 10
	s_add_i32 m0, s27, s28
	s_nop 0
	global_load_lds_dwordx4 v[236:237], off
	s_branch .Lpf_done
.Lpf_ssq:
	s_sub_u32 s28, s0, s92
	s_lshr_b32 s28, s28, 12
	s_add_i32 s28, s28, -2
	s_sub_i32 s29, s26, 4
	s_lshl_b32 s30, s29, 7
	s_add_i32 s28, s28, s30
	v_lshlrev_b32_e32 v236, 1, v235
	v_add_u32_e32 v236, s28, v236
	v_cmp_gt_u32_e32 vcc, 0x1fff, v236
	s_nop 1
	v_cndmask_b32_e32 v236, 0, v236, vcc
	v_lshlrev_b32_e32 v236, 3, v236
	v_mov_b32_e32 v237, 0
	v_lshl_add_u64 v[236:237], s[18:19], 0, v[236:237]
	s_lshl_b32 s29, s29, 10
	s_add_i32 s29, s29, 0x1000
	s_add_i32 m0, s27, s29
	s_nop 0
	global_load_lds_dwordx4 v[236:237], off
; #define PG8_STAGE(bufoff, gbase, voff) do { _Pragma("unroll") for (int _i = 0; _i < 2; ++_i) \
;         __builtin_amdgcn_global_load_lds((const unsigned*)((const char*)(gbase) + (voff)[_i]), (LAS unsigned*)(lds + (bufoff) + ldsw + _i * 8192), 16, 0, 0); } while (0)
; #define PG8_LDA(dst, b, h) do { _Pragma("unroll") for (int m = 0; m < 4; ++m) _Pragma("unroll") for (int k = 0; k < 2; ++k) dst[m][k] = *(const LAS bf16x8*)(lds + PG8_SA(b, h) + aoff + m * 2048 + k * 1024); } while (0)
; #define PG8_LDB(dst, b, h) do { _Pragma("unroll") for (int n = 0; n < 2; ++n) _Pragma("unroll") for (int k = 0; k < 2; ++k) dst[n][k] = *(const LAS bf16x8*)(lds + PG8_SB(b, h) + boff + n * 2048 + k * 1024); } while (0)
; #define PG8_MMA(ai, bj, At, Bt) do { __builtin_amdgcn_s_setprio(1); _Pragma("unroll") for (int m = 0; m < 4; ++m) _Pragma("unroll") for (int n = 0; n < 2; ++n) _Pragma("unroll") for (int k = 0; k < 2; ++k) \
;         acc[ai][bj][m][n] = __builtin_amdgcn_mfma_f32_16x16x32_bf16(Bt[n][k], At[m][k], acc[ai][bj][m][n], 0, 0, 0); __builtin_amdgcn_s_setprio(0); } while (0)
; #define PG8_BAR __builtin_amdgcn_s_barrier()
; template <class Epi, class Sched, bool APERM = false, bool HALFN = false>
; __device__ __forceinline__ void gemm_phase(LAS unsigned char* lds, const int tid_in, const int K, const Sched& S, const Epi& E) {
;     ...
;         const bool has_next = S.next(ui + 1, nxt);
;         const char* nA = has_next ? nxt.A : cA; const char* nB = has_next ? nxt.B : cB;
;         for (int t = 0; t < nt; t += 2) {
;             const bool last = (t == nt - 2);
;             const char* a1 = cA + (size_t)(t + 1) * kstep;
;             const char* a2 = last ? nA : cA + (size_t)(t + 2) * kstep; const char* b2 = last ? nB : cB + (size_t)(t + 2) * kstep;
;             const char* a3 = a2 + kstep; const char* b3 = b2 + kstep;
;             PG8_LDB(B0, 0, 0); PG8_LDB(B1, 0, 1); PG8_SCHED; PG8_LDA(At, 0, 0); PG8_STAGE(PG8_SA(1, 1), a1 + hstepA, voffA);
;             PG8_WAIT_V(8); PG8_WAIT_L(0); PG8_BAR; PG8_MMA(0, 0, At, B0); if constexpr (!HALFN) PG8_MMA(0, 1, At, B1); PG8_BAR; PG8_SCHED;
;             PG8_LDA(At, 0, 1); PG8_STAGE(PG8_SB(0, 0), b2, voffB); PG8_STAGE(PG8_SB(0, 1), b2 + hstep, voffB); PG8_STAGE(PG8_SA(0, 0), a2, voffA);
;             PG8_WAIT_V(8); PG8_WAIT_L(0); PG8_BAR; PG8_MMA(1, 0, At, B0); if constexpr (!HALFN) PG8_MMA(1, 1, At, B1); PG8_BAR; PG8_SCHED;
.Lpf_done:
.LBB0_902:
	s_add_u32 s4, s0, 0x100
	s_addc_u32 s5, s1, 0
	s_add_i32 s14, 0, 0x10000
	s_cmp_eq_u32 s13, 28
	s_cselect_b32 s9, s23, s5
	s_cselect_b32 s8, s22, s4
	v_add_u32_e32 v52, s14, v202
	s_cselect_b32 s7, s25, s12
	s_cselect_b32 s6, s24, s11
	s_add_i32 s15, 0, 0x14000
	ds_read_b128 v[62:65], v52
	ds_read_b128 v[128:131], v52 offset:1024
	ds_read_b128 v[132:135], v52 offset:2048
	ds_read_b128 v[136:139], v52 offset:3072
	v_add_u32_e32 v52, s15, v202
	ds_read_b128 v[140:143], v52
	ds_read_b128 v[152:155], v52 offset:1024
	ds_read_b128 v[156:159], v52 offset:2048
	ds_read_b128 v[160:163], v52 offset:3072
	v_lshl_add_u64 v[52:53], s[0:1], 0, v[214:215]
	s_add_i32 m0, s57, 0xc000
	ds_read_b128 v[164:167], v243
	ds_read_b128 v[168:171], v243 offset:1024
	ds_read_b128 v[172:175], v243 offset:2048
	ds_read_b128 v[176:179], v243 offset:3072
	ds_read_b128 v[180:183], v243 offset:4096
	ds_read_b128 v[184:187], v243 offset:5120
	ds_read_b128 v[188:191], v243 offset:6144
	ds_read_b128 v[192:195], v243 offset:7168
	global_load_lds_dwordx4 v[52:53], off
	v_lshl_add_u64 v[52:53], s[0:1], 0, v[212:213]
	s_add_i32 m0, s57, 0xe000
	s_nop 0
	global_load_lds_dwordx4 v[52:53], off
	s_waitcnt vmcnt(8)
	s_waitcnt lgkmcnt(0)
	s_barrier
	s_setprio 1
	s_waitcnt lgkmcnt(0)
	v_mfma_f32_16x16x32_bf16 v[148:151], v[62:65], v[164:167], v[148:151]
	v_mfma_f32_16x16x32_bf16 v[58:61], v[132:135], v[164:167], v[58:61]
	v_mfma_f32_16x16x32_bf16 v[124:127], v[62:65], v[172:175], v[124:127]
	v_mfma_f32_16x16x32_bf16 v[36:39], v[132:135], v[172:175], v[36:39]
	v_mfma_f32_16x16x32_bf16 v[116:119], v[62:65], v[180:183], v[116:119]
	v_mfma_f32_16x16x32_bf16 v[28:31], v[132:135], v[180:183], v[28:31]
	v_mfma_f32_16x16x32_bf16 v[108:111], v[62:65], v[188:191], v[108:111]
	v_mfma_f32_16x16x32_bf16 v[20:23], v[132:135], v[188:191], v[20:23]
	v_mfma_f32_16x16x32_bf16 v[148:151], v[128:131], v[168:171], v[148:151]
	v_mfma_f32_16x16x32_bf16 v[58:61], v[136:139], v[168:171], v[58:61]
	v_mfma_f32_16x16x32_bf16 v[124:127], v[128:131], v[176:179], v[124:127]
	v_mfma_f32_16x16x32_bf16 v[36:39], v[136:139], v[176:179], v[36:39]
	v_mfma_f32_16x16x32_bf16 v[116:119], v[128:131], v[184:187], v[116:119]
	v_mfma_f32_16x16x32_bf16 v[28:31], v[136:139], v[184:187], v[28:31]
	v_mfma_f32_16x16x32_bf16 v[108:111], v[128:131], v[192:195], v[108:111]
	v_mfma_f32_16x16x32_bf16 v[20:23], v[136:139], v[192:195], v[20:23]
	s_setprio 0
	s_setprio 1
	v_mfma_f32_16x16x32_bf16 v[144:147], v[140:143], v[164:167], v[144:147]
	v_mfma_f32_16x16x32_bf16 v[40:43], v[156:159], v[164:167], v[40:43]
	v_mfma_f32_16x16x32_bf16 v[120:123], v[140:143], v[172:175], v[120:123]
	v_mfma_f32_16x16x32_bf16 v[32:35], v[156:159], v[172:175], v[32:35]
	v_mfma_f32_16x16x32_bf16 v[112:115], v[140:143], v[180:183], v[112:115]
	v_mfma_f32_16x16x32_bf16 v[24:27], v[156:159], v[180:183], v[24:27]
	v_mfma_f32_16x16x32_bf16 v[104:107], v[140:143], v[188:191], v[104:107]
	v_mfma_f32_16x16x32_bf16 v[16:19], v[156:159], v[188:191], v[16:19]
	v_mfma_f32_16x16x32_bf16 v[144:147], v[152:155], v[168:171], v[144:147]
	v_mfma_f32_16x16x32_bf16 v[40:43], v[160:163], v[168:171], v[40:43]
	v_mfma_f32_16x16x32_bf16 v[120:123], v[152:155], v[176:179], v[120:123]
	v_mfma_f32_16x16x32_bf16 v[32:35], v[160:163], v[176:179], v[32:35]
	v_mfma_f32_16x16x32_bf16 v[112:115], v[152:155], v[184:187], v[112:115]
	v_mfma_f32_16x16x32_bf16 v[24:27], v[160:163], v[184:187], v[24:27]
	v_mfma_f32_16x16x32_bf16 v[104:107], v[152:155], v[192:195], v[104:107]
	v_mfma_f32_16x16x32_bf16 v[16:19], v[160:163], v[192:195], v[16:19]
	s_setprio 0
	s_barrier
	s_add_i32 s0, s14, s39
	v_lshl_add_u64 v[196:197], s[6:7], 0, v[206:207]
	s_mov_b32 m0, s0
	ds_read_b128 v[164:167], v243 offset:16384
	ds_read_b128 v[168:171], v243 offset:17408
	ds_read_b128 v[172:175], v243 offset:18432
	ds_read_b128 v[176:179], v243 offset:19456
	ds_read_b128 v[180:183], v243 offset:20480
	ds_read_b128 v[184:187], v243 offset:21504
	ds_read_b128 v[188:191], v243 offset:22528
	ds_read_b128 v[192:195], v243 offset:23552
	global_load_lds_dwordx4 v[196:197], off
	s_add_i32 m0, s0, 0x2000
	s_add_u32 s0, s6, 0x80000
	v_lshl_add_u64 v[198:199], s[6:7], 0, v[210:211]
	s_addc_u32 s1, s7, 0
	s_add_i32 s14, s15, s39
	global_load_lds_dwordx4 v[198:199], off
	v_lshl_add_u64 v[52:53], s[0:1], 0, v[206:207]
	s_mov_b32 m0, s14
	v_lshl_add_u64 v[216:217], s[8:9], 0, v[204:205]
	global_load_lds_dwordx4 v[52:53], off
	v_lshl_add_u64 v[52:53], s[0:1], 0, v[210:211]
	s_add_i32 m0, s14, 0x2000
	v_lshl_add_u64 v[218:219], s[8:9], 0, v[208:209]
	global_load_lds_dwordx4 v[52:53], off
	s_mov_b32 m0, s57
	s_nop 0
	global_load_lds_dwordx4 v[216:217], off
	s_mov_b32 m0, s70
	s_nop 0
	global_load_lds_dwordx4 v[218:219], off
	s_waitcnt vmcnt(8)
	s_waitcnt lgkmcnt(0)
	s_barrier
; #define PG8_STAGE(bufoff, gbase, voff) do { _Pragma("unroll") for (int _i = 0; _i < 2; ++_i) \
;         __builtin_amdgcn_global_load_lds((const unsigned*)((const char*)(gbase) + (voff)[_i]), (LAS unsigned*)(lds + (bufoff) + ldsw + _i * 8192), 16, 0, 0); } while (0)
; #define PG8_LDA(dst, b, h) do { _Pragma("unroll") for (int m = 0; m < 4; ++m) _Pragma("unroll") for (int k = 0; k < 2; ++k) dst[m][k] = *(const LAS bf16x8*)(lds + PG8_SA(b, h) + aoff + m * 2048 + k * 1024); } while (0)
; #define PG8_LDB(dst, b, h) do { _Pragma("unroll") for (int n = 0; n < 2; ++n) _Pragma("unroll") for (int k = 0; k < 2; ++k) dst[n][k] = *(const LAS bf16x8*)(lds + PG8_SB(b, h) + boff + n * 2048 + k * 1024); } while (0)
; #define PG8_MMA(ai, bj, At, Bt) do { __builtin_amdgcn_s_setprio(1); _Pragma("unroll") for (int m = 0; m < 4; ++m) _Pragma("unroll") for (int n = 0; n < 2; ++n) _Pragma("unroll") for (int k = 0; k < 2; ++k) \
;         acc[ai][bj][m][n] = __builtin_amdgcn_mfma_f32_16x16x32_bf16(Bt[n][k], At[m][k], acc[ai][bj][m][n], 0, 0, 0); __builtin_amdgcn_s_setprio(0); } while (0)
; #define PG8_WAIT_V(n) asm volatile("s_waitcnt vmcnt(" #n ")" ::: "memory")
; #define PG8_WAIT_L(n) asm volatile("s_waitcnt lgkmcnt(" #n ")" ::: "memory")
; #define PG8_BAR __builtin_amdgcn_s_barrier()
; #define PG8_SCHED __builtin_amdgcn_sched_barrier(0)
; template <class Epi, class Sched, bool APERM = false, bool HALFN = false>
; __device__ __forceinline__ void gemm_phase(LAS unsigned char* lds, const int tid_in, const int K, const Sched& S, const Epi& E) {
;     ...
;             PG8_WAIT_V(8); PG8_WAIT_L(0); PG8_BAR; PG8_MMA(1, 0, At, B0); if constexpr (!HALFN) PG8_MMA(1, 1, At, B1); PG8_BAR; PG8_SCHED;
;             PG8_LDB(B0, 1, 0); PG8_LDB(B1, 1, 1); PG8_SCHED; PG8_LDA(At, 1, 0); PG8_STAGE(PG8_SA(0, 1), a2 + hstepA, voffA);
;             PG8_WAIT_V(8); PG8_WAIT_L(0); PG8_BAR; PG8_MMA(0, 0, At, B0); if constexpr (!HALFN) PG8_MMA(0, 1, At, B1); PG8_BAR; PG8_SCHED;
	s_setprio 1
	s_waitcnt lgkmcnt(0)
	v_mfma_f32_16x16x32_bf16 v[100:103], v[62:65], v[164:167], v[100:103]
	v_mfma_f32_16x16x32_bf16 v[12:15], v[132:135], v[164:167], v[12:15]
	v_mfma_f32_16x16x32_bf16 v[92:95], v[62:65], v[172:175], v[92:95]
	v_mfma_f32_16x16x32_bf16 v[4:7], v[132:135], v[172:175], v[4:7]
	v_mfma_f32_16x16x32_bf16 v[48:51], v[62:65], v[180:183], v[48:51]
	v_mfma_f32_16x16x32_bf16 v[72:75], v[132:135], v[180:183], v[72:75]
	v_mfma_f32_16x16x32_bf16 v[66:69], v[132:135], v[188:191], v[68:71]
	v_mfma_f32_16x16x32_bf16 v[100:103], v[128:131], v[168:171], v[100:103]
	v_mfma_f32_16x16x32_bf16 v[12:15], v[136:139], v[168:171], v[12:15]
	v_mfma_f32_16x16x32_bf16 v[92:95], v[128:131], v[176:179], v[92:95]
	v_mfma_f32_16x16x32_bf16 v[4:7], v[136:139], v[176:179], v[4:7]
	v_mfma_f32_16x16x32_bf16 v[48:51], v[128:131], v[184:187], v[48:51]
	v_mfma_f32_16x16x32_bf16 v[72:75], v[136:139], v[184:187], v[72:75]
	v_mfma_f32_16x16x32_bf16 v[62:65], v[62:65], v[188:191], v[80:83]
	v_mfma_f32_16x16x32_bf16 v[66:69], v[136:139], v[192:195], v[66:69]
	v_mfma_f32_16x16x32_bf16 v[62:65], v[128:131], v[192:195], v[62:65]
	s_setprio 0
	s_setprio 1
	v_mfma_f32_16x16x32_bf16 v[80:83], v[140:143], v[164:167], v[96:99]
	v_mfma_f32_16x16x32_bf16 v[96:99], v[152:155], v[168:171], v[80:83]
	v_mfma_f32_16x16x32_bf16 v[80:83], v[140:143], v[172:175], v[88:91]
	v_mfma_f32_16x16x32_bf16 v[8:11], v[156:159], v[164:167], v[8:11]
	v_mfma_f32_16x16x32_bf16 v[88:91], v[152:155], v[176:179], v[80:83]
	v_mfma_f32_16x16x32_bf16 v[0:3], v[156:159], v[172:175], v[0:3]
	v_mfma_f32_16x16x32_bf16 v[80:83], v[140:143], v[180:183], v[84:87]
	v_mfma_f32_16x16x32_bf16 v[52:55], v[156:159], v[180:183], v[54:57]
	v_mfma_f32_16x16x32_bf16 v[76:79], v[140:143], v[188:191], v[76:79]
	v_mfma_f32_16x16x32_bf16 v[44:47], v[156:159], v[188:191], v[44:47]
	v_mfma_f32_16x16x32_bf16 v[8:11], v[160:163], v[168:171], v[8:11]
	v_mfma_f32_16x16x32_bf16 v[0:3], v[160:163], v[176:179], v[0:3]
	v_mfma_f32_16x16x32_bf16 v[84:87], v[152:155], v[184:187], v[80:83]
	v_mfma_f32_16x16x32_bf16 v[52:55], v[160:163], v[184:187], v[52:55]
	v_mfma_f32_16x16x32_bf16 v[76:79], v[152:155], v[192:195], v[76:79]
	v_mfma_f32_16x16x32_bf16 v[44:47], v[160:163], v[192:195], v[44:47]
	s_setprio 0
	s_barrier
	s_add_i32 s14, 0, 0x18000
	v_add_u32_e32 v56, s14, v202
	s_add_i32 s15, 0, 0x1c000
	ds_read_b128 v[80:83], v56
	ds_read_b128 v[128:131], v56 offset:1024
	ds_read_b128 v[132:135], v56 offset:2048
	ds_read_b128 v[136:139], v56 offset:3072
	v_add_u32_e32 v56, s15, v202
	ds_read_b128 v[140:143], v56
	ds_read_b128 v[152:155], v56 offset:1024
	ds_read_b128 v[156:159], v56 offset:2048
	ds_read_b128 v[160:163], v56 offset:3072
	s_add_u32 s0, s8, 0x4000
	s_addc_u32 s1, s9, 0
	s_mov_b32 m0, s71
	v_lshl_add_u64 v[56:57], s[0:1], 0, v[204:205]
	ds_read_b128 v[164:167], v243 offset:32768
	ds_read_b128 v[168:171], v243 offset:33792
	ds_read_b128 v[172:175], v243 offset:34816
	ds_read_b128 v[176:179], v243 offset:35840
	ds_read_b128 v[180:183], v243 offset:36864
	ds_read_b128 v[184:187], v243 offset:37888
	ds_read_b128 v[188:191], v243 offset:38912
	ds_read_b128 v[192:195], v243 offset:39936
	global_load_lds_dwordx4 v[56:57], off
	v_lshl_add_u64 v[56:57], s[0:1], 0, v[208:209]
	s_mov_b32 m0, s72
	s_nop 0
	global_load_lds_dwordx4 v[56:57], off
	s_waitcnt vmcnt(8)
	s_waitcnt lgkmcnt(0)
	s_barrier
	s_setprio 1
	s_waitcnt lgkmcnt(0)
	v_mfma_f32_16x16x32_bf16 v[148:151], v[80:83], v[164:167], v[148:151]
	v_mfma_f32_16x16x32_bf16 v[56:59], v[132:135], v[164:167], v[58:61]
	v_mfma_f32_16x16x32_bf16 v[124:127], v[80:83], v[172:175], v[124:127]
	v_mfma_f32_16x16x32_bf16 v[36:39], v[132:135], v[172:175], v[36:39]
	v_mfma_f32_16x16x32_bf16 v[116:119], v[80:83], v[180:183], v[116:119]
	v_mfma_f32_16x16x32_bf16 v[28:31], v[132:135], v[180:183], v[28:31]
	v_mfma_f32_16x16x32_bf16 v[108:111], v[80:83], v[188:191], v[108:111]
	v_mfma_f32_16x16x32_bf16 v[20:23], v[132:135], v[188:191], v[20:23]
	v_mfma_f32_16x16x32_bf16 v[148:151], v[128:131], v[168:171], v[148:151]
	v_mfma_f32_16x16x32_bf16 v[58:61], v[136:139], v[168:171], v[56:59]
	v_mfma_f32_16x16x32_bf16 v[124:127], v[128:131], v[176:179], v[124:127]
	v_mfma_f32_16x16x32_bf16 v[36:39], v[136:139], v[176:179], v[36:39]
	v_mfma_f32_16x16x32_bf16 v[116:119], v[128:131], v[184:187], v[116:119]
	v_mfma_f32_16x16x32_bf16 v[28:31], v[136:139], v[184:187], v[28:31]
	v_mfma_f32_16x16x32_bf16 v[108:111], v[128:131], v[192:195], v[108:111]
	v_mfma_f32_16x16x32_bf16 v[20:23], v[136:139], v[192:195], v[20:23]
	s_setprio 0
	s_setprio 1
	v_mfma_f32_16x16x32_bf16 v[144:147], v[140:143], v[164:167], v[144:147]
	v_mfma_f32_16x16x32_bf16 v[40:43], v[156:159], v[164:167], v[40:43]
	v_mfma_f32_16x16x32_bf16 v[120:123], v[140:143], v[172:175], v[120:123]
	v_mfma_f32_16x16x32_bf16 v[32:35], v[156:159], v[172:175], v[32:35]
	v_mfma_f32_16x16x32_bf16 v[112:115], v[140:143], v[180:183], v[112:115]
	v_mfma_f32_16x16x32_bf16 v[24:27], v[156:159], v[180:183], v[24:27]
	v_mfma_f32_16x16x32_bf16 v[104:107], v[140:143], v[188:191], v[104:107]
	v_mfma_f32_16x16x32_bf16 v[16:19], v[156:159], v[188:191], v[16:19]
	v_mfma_f32_16x16x32_bf16 v[144:147], v[152:155], v[168:171], v[144:147]
	v_mfma_f32_16x16x32_bf16 v[40:43], v[160:163], v[168:171], v[40:43]
	v_mfma_f32_16x16x32_bf16 v[120:123], v[152:155], v[176:179], v[120:123]
	v_mfma_f32_16x16x32_bf16 v[32:35], v[160:163], v[176:179], v[32:35]
	v_mfma_f32_16x16x32_bf16 v[112:115], v[152:155], v[184:187], v[112:115]
	v_mfma_f32_16x16x32_bf16 v[24:27], v[160:163], v[184:187], v[24:27]
	v_mfma_f32_16x16x32_bf16 v[104:107], v[152:155], v[192:195], v[104:107]
	v_mfma_f32_16x16x32_bf16 v[16:19], v[160:163], v[192:195], v[16:19]
	s_setprio 0
	s_barrier
; #define PG8_STAGE(bufoff, gbase, voff) do { _Pragma("unroll") for (int _i = 0; _i < 2; ++_i) \
;         __builtin_amdgcn_global_load_lds((const unsigned*)((const char*)(gbase) + (voff)[_i]), (LAS unsigned*)(lds + (bufoff) + ldsw + _i * 8192), 16, 0, 0); } while (0)
; #define PG8_LDA(dst, b, h) do { _Pragma("unroll") for (int m = 0; m < 4; ++m) _Pragma("unroll") for (int k = 0; k < 2; ++k) dst[m][k] = *(const LAS bf16x8*)(lds + PG8_SA(b, h) + aoff + m * 2048 + k * 1024); } while (0)
; #define PG8_MMA(ai, bj, At, Bt) do { __builtin_amdgcn_s_setprio(1); _Pragma("unroll") for (int m = 0; m < 4; ++m) _Pragma("unroll") for (int n = 0; n < 2; ++n) _Pragma("unroll") for (int k = 0; k < 2; ++k) \
;         acc[ai][bj][m][n] = __builtin_amdgcn_mfma_f32_16x16x32_bf16(Bt[n][k], At[m][k], acc[ai][bj][m][n], 0, 0, 0); __builtin_amdgcn_s_setprio(0); } while (0)
; #define PG8_WAIT_V(n) asm volatile("s_waitcnt vmcnt(" #n ")" ::: "memory")
; #define PG8_WAIT_L(n) asm volatile("s_waitcnt lgkmcnt(" #n ")" ::: "memory")
; #define PG8_BAR __builtin_amdgcn_s_barrier()
; #define PG8_SCHED __builtin_amdgcn_sched_barrier(0)
;     __device__ __forceinline__ CU2 full(int i) const { const int Lx = i * G + c; CU2 u; tile_order(Lx, 33, 44, u.pm, u.pn); return u; }
; template <class Epi, class Sched, bool APERM = false, bool HALFN = false>
; __device__ __forceinline__ void gemm_phase(LAS unsigned char* lds, const int tid_in, const int K, const Sched& S, const Epi& E) {
;     ...
;             PG8_LDA(At, 1, 1); PG8_STAGE(PG8_SB(1, 0), b3, voffB); PG8_STAGE(PG8_SB(1, 1), b3 + hstep, voffB); PG8_STAGE(PG8_SA(1, 0), a3, voffA);
;             PG8_WAIT_V(8); PG8_WAIT_L(0); PG8_BAR; PG8_MMA(1, 0, At, B0); if constexpr (!HALFN) PG8_MMA(1, 1, At, B1); PG8_BAR; PG8_SCHED;
;         }
;         if (wr == 0) PG8_BAR;
;         { const Unit fu = S.full(ui); E(acc, fu, wr, wc, fr, fq); }
	s_add_i32 s0, s14, s39
	v_lshl_add_u64 v[56:57], v[196:197], 0, s[78:79]
	s_mov_b32 m0, s0
	ds_read_b128 v[164:167], v243 offset:49152
	ds_read_b128 v[168:171], v243 offset:50176
	ds_read_b128 v[172:175], v243 offset:51200
	ds_read_b128 v[176:179], v243 offset:52224
	ds_read_b128 v[180:183], v243 offset:53248
	ds_read_b128 v[184:187], v243 offset:54272
	ds_read_b128 v[188:191], v243 offset:55296
	ds_read_b128 v[192:195], v243 offset:56320
	global_load_lds_dwordx4 v[56:57], off
	s_add_i32 m0, s0, 0x2000
	s_add_u32 s0, s6, 0x80080
	v_lshl_add_u64 v[56:57], v[198:199], 0, s[78:79]
	s_addc_u32 s1, s7, 0
	s_add_i32 s6, s15, s39
	global_load_lds_dwordx4 v[56:57], off
	v_lshl_add_u64 v[56:57], s[0:1], 0, v[206:207]
	s_mov_b32 m0, s6
	s_nop 0
	global_load_lds_dwordx4 v[56:57], off
	v_lshl_add_u64 v[56:57], s[0:1], 0, v[210:211]
	s_add_i32 m0, s6, 0x2000
	s_nop 0
	global_load_lds_dwordx4 v[56:57], off
	v_lshl_add_u64 v[56:57], v[216:217], 0, s[78:79]
	s_mov_b32 m0, s81
	s_nop 0
	global_load_lds_dwordx4 v[56:57], off
	v_lshl_add_u64 v[56:57], v[218:219], 0, s[78:79]
	s_mov_b32 m0, s86
	s_nop 0
	global_load_lds_dwordx4 v[56:57], off
	s_waitcnt vmcnt(8)
	s_waitcnt lgkmcnt(0)
	s_barrier
	s_setprio 1
	s_waitcnt lgkmcnt(0)
	v_mfma_f32_16x16x32_bf16 v[62:65], v[80:83], v[188:191], v[62:65]
	v_mfma_f32_16x16x32_bf16 v[100:103], v[80:83], v[164:167], v[100:103]
	v_mfma_f32_16x16x32_bf16 v[12:15], v[132:135], v[164:167], v[12:15]
	v_mfma_f32_16x16x32_bf16 v[92:95], v[80:83], v[172:175], v[92:95]
	v_mfma_f32_16x16x32_bf16 v[4:7], v[132:135], v[172:175], v[4:7]
	v_mfma_f32_16x16x32_bf16 v[48:51], v[80:83], v[180:183], v[48:51]
	v_mfma_f32_16x16x32_bf16 v[70:73], v[132:135], v[180:183], v[72:75]
	v_mfma_f32_16x16x32_bf16 v[80:83], v[128:131], v[192:195], v[62:65]
	v_mfma_f32_16x16x32_bf16 v[62:65], v[132:135], v[188:191], v[66:69]
	v_mfma_f32_16x16x32_bf16 v[100:103], v[128:131], v[168:171], v[100:103]
	v_mfma_f32_16x16x32_bf16 v[12:15], v[136:139], v[168:171], v[12:15]
	v_mfma_f32_16x16x32_bf16 v[92:95], v[128:131], v[176:179], v[92:95]
	v_mfma_f32_16x16x32_bf16 v[4:7], v[136:139], v[176:179], v[4:7]
	v_mfma_f32_16x16x32_bf16 v[48:51], v[128:131], v[184:187], v[48:51]
	v_mfma_f32_16x16x32_bf16 v[72:75], v[136:139], v[184:187], v[70:73]
	v_mfma_f32_16x16x32_bf16 v[68:71], v[136:139], v[192:195], v[62:65]
	s_setprio 0
	s_setprio 1
	v_mfma_f32_16x16x32_bf16 v[62:65], v[140:143], v[164:167], v[96:99]
	v_mfma_f32_16x16x32_bf16 v[96:99], v[152:155], v[168:171], v[62:65]
	v_mfma_f32_16x16x32_bf16 v[62:65], v[140:143], v[172:175], v[88:91]
	v_mfma_f32_16x16x32_bf16 v[88:91], v[152:155], v[176:179], v[62:65]
	v_mfma_f32_16x16x32_bf16 v[62:65], v[140:143], v[180:183], v[84:87]
	v_mfma_f32_16x16x32_bf16 v[8:11], v[156:159], v[164:167], v[8:11]
	v_mfma_f32_16x16x32_bf16 v[0:3], v[156:159], v[172:175], v[0:3]
	v_mfma_f32_16x16x32_bf16 v[84:87], v[152:155], v[184:187], v[62:65]
	v_mfma_f32_16x16x32_bf16 v[52:55], v[156:159], v[180:183], v[52:55]
	v_mfma_f32_16x16x32_bf16 v[62:65], v[140:143], v[188:191], v[76:79]
	v_mfma_f32_16x16x32_bf16 v[44:47], v[156:159], v[188:191], v[44:47]
	v_mfma_f32_16x16x32_bf16 v[8:11], v[160:163], v[168:171], v[8:11]
	v_mfma_f32_16x16x32_bf16 v[0:3], v[160:163], v[176:179], v[0:3]
	v_mfma_f32_16x16x32_bf16 v[54:57], v[160:163], v[184:187], v[52:55]
	v_mfma_f32_16x16x32_bf16 v[76:79], v[152:155], v[192:195], v[62:65]
	v_mfma_f32_16x16x32_bf16 v[44:47], v[160:163], v[192:195], v[44:47]
	s_setprio 0
	s_barrier
	s_add_i32 s13, s13, 2
	s_add_u32 s11, s11, 0x100
	s_addc_u32 s12, s12, 0
	s_cmp_gt_u32 s13, 29
	s_mov_b64 s[0:1], s[4:5]
	s_cbranch_scc0 .LBB0_902
	s_and_b64 vcc, exec, s[16:17]
	s_cbranch_vccz .LBB0_905
	s_barrier
.LBB0_905:
	s_and_b32 s32, s10, 1
	s_mulk_i32 s32, 0x1800
	s_add_i32 s32, s32, 0x20800
	s_mul_i32 s0, s10, s38
	s_add_i32 s0, s0, s35
	s_ashr_i32 s1, s0, 31
	s_lshr_b32 s1, s1, 29
	s_add_i32 s4, s0, s1
	s_and_b32 s1, s4, -8
	s_sub_i32 s5, s0, s1
	s_cmp_gt_i32 s5, 3
	s_mov_b64 s[0:1], -1
	s_cbranch_scc0 .LBB0_907
	s_mul_i32 s0, s5, 0xb5
	s_add_i32 s6, s0, 4
	s_mov_b64 s[0:1], 0

; __device__ __forceinline__ float u64f(u64 q) { return (float)(unsigned)(q >> 32) * 4294967296.f + (float)(unsigned)q; }
;     __device__ __forceinline__ void operator()(const f32x4 (&acc)[2][2][4][2], const CU2& u, int wr, int wc, int fr_, int fq_) const {
;         int ln0 = (int)__builtin_amdgcn_mbcnt_hi(~0u, __builtin_amdgcn_mbcnt_lo(~0u, 0u)); asm volatile("" : "+v"(ln0)); const int fr = ln0 & 15, fq = ln0 >> 4;
;         int cl = 32 * wc + 8 * fq, rb = 128 * wr + 8 * fr; asm volatile("" : "+v"(cl), "+v"(rb));
;         const int t0 = 254 * u.pm - 2, tb = t0 + rb;
;         const u64* ssq = (const u64*)(ws + WS_SSQ) + (3 * l + 2) * T_; const float* cw = p.conv_w + (size_t)l * 3 * 2 * FF_; const float* cb = p.conv_b + (size_t)l * 2 * FF_; bf16_t* act = (bf16_t*)(ws + WS_ACT);
;         float rsv[8];
;         { u64 q_[8];
; #pragma unroll
;           for (int j = 0; j < 8; ++j) q_[j] = ssq[(unsigned)(tb + j) < (unsigned)T_ ? tb + j : 0];
; #pragma unroll
;           for (int j = 0; j < 8; ++j) rsv[j] = (unsigned)(tb + j) < (unsigned)T_ ? rsqrtf(u64f(q_[j]) * SSQ_INV + EPS) : 0.f; }
.LBB0_909:
	s_ashr_i32 s0, s4, 3
	s_add_i32 s0, s6, s0
	s_mul_hi_i32 s1, s0, 0x2e8ba2e9
	s_lshr_b32 s4, s1, 31
	s_ashr_i32 s1, s1, 6
	s_add_i32 s1, s1, s4
	s_lshl_b32 s4, s1, 3
	s_sub_i32 s5, 33, s4
	s_min_i32 s5, s5, 8
	s_abs_i32 s6, s5
	v_cvt_f32_u32_e32 v52, s6
	s_sub_i32 s8, 0, s6
	s_mulk_i32 s1, 0x160
	s_sub_i32 s0, s0, s1
	v_rcp_iflag_f32_e32 v52, v52
	s_abs_i32 s1, s0
	s_xor_b32 s7, s0, s5
	s_ashr_i32 s7, s7, 31
	v_mul_f32_e32 v52, 0x4f7ffffe, v52
	v_cvt_u32_f32_e32 v52, v52
	v_mov_b32_e32 v224, 0
	v_mov_b32_e32 v228, 0
	v_readfirstlane_b32 s9, v52
	s_mul_i32 s8, s8, s9
	s_mul_hi_u32 s8, s9, s8
	s_add_i32 s9, s9, s8
	s_mul_hi_u32 s8, s1, s9
	s_mul_i32 s9, s8, s6
	s_sub_i32 s1, s1, s9
	s_add_i32 s10, s8, 1
	s_sub_i32 s9, s1, s6
	s_cmp_ge_u32 s1, s6
	s_cselect_b32 s8, s10, s8
	s_cselect_b32 s1, s9, s1
	s_add_i32 s9, s8, 1
	s_cmp_ge_u32 s1, s6
	s_cselect_b32 s1, s9, s8
	s_xor_b32 s1, s1, s7
	s_sub_i32 s28, s1, s7
	v_mov_b32_e32 v52, v235
	s_mul_i32 s1, s28, s5
	s_sub_i32 s0, s0, s1
	v_and_b32_e32 v184, 15, v52
	v_ashrrev_i32_e32 v52, 1, v52
	s_add_i32 s0, s4, s0
	v_and_b32_e32 v52, -8, v52
	v_add_u32_e32 v226, s80, v52
	v_lshl_or_b32 v225, v184, 3, s87
	v_lshl_add_u32 v236, v225, 3, s32
	v_lshl_add_u32 v237, v226, 2, s32
	v_add_u32_e32 v236, 0x1000, v236
	s_mulk_i32 s0, 0xfe
	s_nop 0
	v_add_u32_e32 v221, s0, v225
	v_add_u32_e32 v223, -1, v221
	v_add_u32_e32 v217, 2, v221
	v_cmp_gt_u32_e64 s[10:11], s89, v223
	v_cmp_gt_u32_e64 s[8:9], s89, v221
	v_add_u32_e32 v219, 1, v221
	v_cmp_gt_u32_e64 s[4:5], s89, v217
	v_cndmask_b32_e64 v52, 0, v223, s[10:11]
	v_cndmask_b32_e64 v62, 0, v221, s[8:9]
	v_cmp_gt_u32_e64 s[6:7], s89, v219
	v_cndmask_b32_e64 v66, 0, v217, s[4:5]
	v_ashrrev_i32_e32 v53, 31, v52
	v_ashrrev_i32_e32 v63, 31, v62
	v_cndmask_b32_e64 v64, 0, v219, s[6:7]
	v_ashrrev_i32_e32 v67, 31, v66
	v_add_u32_e32 v246, 3, v221
	v_add_u32_e32 v245, 4, v221
	v_lshl_add_u64 v[52:53], v[52:53], 3, s[18:19]
	v_lshl_add_u64 v[62:63], v[62:63], 3, s[18:19]
	v_ashrrev_i32_e32 v65, 31, v64
	v_lshl_add_u64 v[66:67], v[66:67], 3, s[18:19]
	v_cmp_gt_u32_e64 s[12:13], s89, v246
	v_cmp_gt_u32_e64 s[0:1], s89, v245
	v_add_u32_e32 v244, 5, v221
	v_lshl_add_u64 v[64:65], v[64:65], 3, s[18:19]
	ds_read_b64 v[132:133], v236 offset:8
	ds_read_b64 v[130:131], v236 offset:16
	ds_read_b64 v[128:129], v236 offset:24
	s_nop 0
	ds_read_b64 v[66:67], v236 offset:32
	v_cndmask_b32_e64 v52, 0, v246, s[12:13]
	v_cndmask_b32_e64 v62, 0, v245, s[0:1]
	v_cmp_gt_u32_e32 vcc, s89, v244
	v_ashrrev_i32_e32 v53, 31, v52
	v_ashrrev_i32_e32 v63, 31, v62
	v_cndmask_b32_e32 v64, 0, v244, vcc
	v_lshl_add_u64 v[52:53], v[52:53], 3, s[18:19]
	v_lshl_add_u64 v[62:63], v[62:63], 3, s[18:19]
	v_ashrrev_i32_e32 v65, 31, v64
	v_lshl_add_u64 v[134:135], v[64:65], 3, s[18:19]
	ds_read_b64 v[64:65], v236 offset:40
	s_nop 0
	ds_read_b64 v[62:63], v236 offset:48
	s_nop 0
	ds_read_b64 v[52:53], v236 offset:56
	v_add_u32_e32 v200, -2, v221
	v_cmp_gt_u32_e64 s[14:15], s89, v200
	s_and_saveexec_b64 s[26:27], s[14:15]
	s_cbranch_execz .LBB0_911
	v_lshl_add_u64 v[134:135], v[200:201], 3, s[18:19]
	ds_read_b64 v[134:135], v236
	v_mov_b32_e32 v137, v201
	s_min_u32 s14, s91, 32
	s_waitcnt vmcnt(0) lgkmcnt(0)
	v_mov_b32_e32 v136, v135
	v_lshlrev_b64 v[136:137], s14, v[136:137]
	v_min_u32_e32 v135, 1, v136
	v_or_b32_e32 v135, v137, v135
	v_cvt_f32_u32_e32 v135, v135
	v_cvt_f32_u32_e32 v134, v134
	s_sub_i32 s14, 32, s14
	v_ldexp_f32 v135, v135, s14
	v_fmac_f32_e32 v134, 0x4f800000, v135
	v_fmamk_f32 v134, v134, 0x2e000000, v240
	v_mul_f32_e32 v135, 0x4b800000, v134
	v_cmp_gt_f32_e64 s[14:15], s85, v134
	s_nop 1
	v_cndmask_b32_e64 v134, v134, v135, s[14:15]
	v_rsq_f32_e32 v134, v134
	s_nop 0
	v_mul_f32_e32 v135, 0x45800000, v134
	v_cndmask_b32_e64 v228, v134, v135, s[14:15]

;     __device__ __forceinline__ void operator()(const f32x4 (&acc)[2][2][4][2], const CU2& u, int wr, int wc, int fr_, int fq_) const {
;     ...
;         asm volatile("s_waitcnt lgkmcnt(0)" ::: "memory"); __builtin_amdgcn_s_barrier(); asm volatile("" ::: "memory");
; #pragma unroll
;         for (int n = 0; n < 2; ++n) {
;             const float* wp = cw + 128 * u.pn + cl + 4 * n; const float* bp = cb + 128 * u.pn + cl + 4 * n;
;             const f32x4 g0 = *(const f32x4*)wp, g1 = *(const f32x4*)(wp + 2 * FF_), g2 = *(const f32x4*)(wp + 4 * FF_), gb = *(const f32x4*)bp;
;             const f32x4 v0 = *(const f32x4*)(wp + FF_), v1 = *(const f32x4*)(wp + 3 * FF_), v2 = *(const f32x4*)(wp + 5 * FF_), vb = *(const f32x4*)(bp + FF_);
;             f32x4 pg2 = acc[1][0][2][n] * rsv[6], pg1 = acc[1][0][3][n] * rsv[7], pv2 = acc[1][1][2][n] * rsv[6], pv1 = acc[1][1][3][n] * rsv[7];
; #pragma unroll
;             for (int e = 0; e < 4; ++e) {
;                 pg2[e] = __int_as_float(__builtin_amdgcn_mov_dpp(__float_as_int(pg2[e]), 0x111, 0xF, 0xF, true)); pg1[e] = __int_as_float(__builtin_amdgcn_mov_dpp(__float_as_int(pg1[e]), 0x111, 0xF, 0xF, true));
;                 pv2[e] = __int_as_float(__builtin_amdgcn_mov_dpp(__float_as_int(pv2[e]), 0x111, 0xF, 0xF, true)); pv1[e] = __int_as_float(__builtin_amdgcn_mov_dpp(__float_as_int(pv1[e]), 0x111, 0xF, 0xF, true));
;             }
;             if (fr == 0 && wr == 1) { pg2 = *(const LAS f32x4*)(hal + cl + 4 * n); pg1 = *(const LAS f32x4*)(hal + 256 + cl + 4 * n); pv2 = *(const LAS f32x4*)(hal + 128 + cl + 4 * n); pv1 = *(const LAS f32x4*)(hal + 384 + cl + 4 * n); }
; #pragma unroll
;             for (int j = 0; j < 8; ++j) {
;                 const f32x4 xg = acc[j >> 2][0][j & 3][n] * rsv[j], xv = acc[j >> 2][1][j & 3][n] * rsv[j];
;                 const f32x4 gc = gb + g2 * xg + g1 * pg1 + g0 * pg2, vc = vb + v2 * xv + v1 * pv1 + v0 * pv2;
;                 f32x4 sg;
; #pragma unroll
;                 for (int e = 0; e < 4; ++e) sg[e] = __builtin_amdgcn_rcpf(1.f + __expf(-gc[e]));
;                 const f32x4 o4 = gc * sg * vc;
;                 pg2 = pg1; pg1 = xg; pv2 = pv1; pv1 = xv;
;                 if (rb + j >= 2 && tb + j < T_) { u32x2 w; w.x = cvt_pk_bf16(o4[0], o4[1]); w.y = cvt_pk_bf16(o4[2], o4[3]); *(u32x2*)(act + (size_t)(tb + j) * FF_ + 128 * u.pn + cl + 4 * n) = w; }
.LBB0_929:
	s_or_b64 exec, exec, s[0:1]
	s_lshl_b32 s0, s28, 7
	s_ashr_i32 s1, s0, 31
	s_lshl_b64 s[4:5], s[0:1], 2
	s_add_u32 s6, s76, s4
	s_addc_u32 s7, s77, s5
	v_ashrrev_i32_e32 v227, 31, v226
	s_add_u32 s4, s74, s4
	v_lshlrev_b64 v[44:45], 2, v[226:227]
	s_addc_u32 s5, s75, s5
	v_lshl_add_u64 v[54:55], s[6:7], 0, v[44:45]
	v_lshl_add_u64 v[44:45], s[4:5], 0, v[44:45]
	s_mov_b32 s4, 0xb000
	v_add_co_u32_e32 v50, vcc, s4, v54
	s_mov_b32 s4, 0x16000
	s_nop 0
	v_addc_co_u32_e32 v51, vcc, 0, v55, vcc
	v_add_co_u32_e32 v64, vcc, s4, v54
	s_waitcnt lgkmcnt(0)
	s_barrier
	s_nop 0
	v_addc_co_u32_e32 v65, vcc, 0, v55, vcc
	s_movk_i32 s5, 0x5000
	ds_read_b128 v[152:155], v237 offset:0
	ds_read_b128 v[160:163], v237 offset:512
	ds_read_b128 v[164:167], v237 offset:1024
	ds_read_b128 v[168:171], v237 offset:1536
	v_add_co_u32_e32 v50, vcc, s5, v54
	s_mov_b32 s4, 0x10000
	s_nop 0
	v_addc_co_u32_e32 v51, vcc, 0, v55, vcc
	v_add_co_u32_e32 v64, vcc, s4, v54
	s_mov_b32 s4, 0x1b000
	s_nop 0
	v_addc_co_u32_e32 v65, vcc, 0, v55, vcc
	v_add_co_u32_e32 v68, vcc, s4, v54
	ds_read_b128 v[172:175], v237 offset:2560
	s_nop 0
	v_addc_co_u32_e32 v69, vcc, 0, v55, vcc
	ds_read_b128 v[156:159], v237 offset:2048
	ds_read_b128 v[176:179], v237 offset:3072
	v_add_co_u32_e32 v50, vcc, s5, v44
	v_mov_b64_e32 v[194:195], v[142:143]
	s_nop 0
	v_addc_co_u32_e32 v51, vcc, 0, v45, vcc
	ds_read_b128 v[180:183], v237 offset:3584
	v_cmp_eq_u32_e32 vcc, 0, v184
	v_mov_b32_dpp v50, v140 row_shr:1 row_mask:0xf bank_mask:0xf bound_ctrl:1
	v_mov_b64_e32 v[192:193], v[140:141]
	s_and_b64 s[4:5], s[2:3], vcc
	v_mov_b32_e32 v192, v50
	v_mov_b32_dpp v184, v128 row_shr:1 row_mask:0xf bank_mask:0xf bound_ctrl:1
	v_mov_b32_dpp v196, v132 row_shr:1 row_mask:0xf bank_mask:0xf bound_ctrl:1
	v_mov_b32_dpp v188, v136 row_shr:1 row_mask:0xf bank_mask:0xf bound_ctrl:1
	v_mov_b32_dpp v193, v141 row_shr:1 row_mask:0xf bank_mask:0xf bound_ctrl:1
	v_mov_b32_dpp v185, v129 row_shr:1 row_mask:0xf bank_mask:0xf bound_ctrl:1
	v_mov_b32_dpp v197, v133 row_shr:1 row_mask:0xf bank_mask:0xf bound_ctrl:1
	v_mov_b32_dpp v189, v137 row_shr:1 row_mask:0xf bank_mask:0xf bound_ctrl:1
	v_mov_b32_dpp v194, v194 row_shr:1 row_mask:0xf bank_mask:0xf bound_ctrl:1
	v_mov_b32_dpp v186, v130 row_shr:1 row_mask:0xf bank_mask:0xf bound_ctrl:1
	v_mov_b32_dpp v198, v134 row_shr:1 row_mask:0xf bank_mask:0xf bound_ctrl:1
	v_mov_b32_dpp v190, v138 row_shr:1 row_mask:0xf bank_mask:0xf bound_ctrl:1
	v_mov_b32_dpp v195, v195 row_shr:1 row_mask:0xf bank_mask:0xf bound_ctrl:1
	v_mov_b32_dpp v187, v131 row_shr:1 row_mask:0xf bank_mask:0xf bound_ctrl:1
	v_mov_b32_dpp v199, v135 row_shr:1 row_mask:0xf bank_mask:0xf bound_ctrl:1
	v_mov_b32_dpp v191, v139 row_shr:1 row_mask:0xf bank_mask:0xf bound_ctrl:1
	s_and_saveexec_b64 s[6:7], s[4:5]
	s_cbranch_execz .LBB0_931
	v_add_u32_e32 v69, 0x20000, v76
	v_add_u32_e32 v50, 0x20600, v76
	v_add_u32_e32 v51, 0x20200, v76
	v_add_u32_e32 v68, 0x20400, v76
	ds_read_b128 v[192:195], v69
	ds_read_b128 v[184:187], v68
	ds_read_b128 v[196:199], v51
	ds_read_b128 v[188:191], v50
.LBB0_931:
	s_or_b64 exec, exec, s[6:7]
	s_lshl_b64 s[0:1], s[0:1], 1
	s_add_u32 s0, s44, s0
	s_addc_u32 s1, s45, s1
	v_lshl_add_u64 v[50:51], v[226:227], 1, s[0:1]
	v_cmp_lt_i32_e32 vcc, 1, v225
	v_cmp_gt_i32_e64 s[0:1], s89, v200
	v_pk_mul_f32 v[80:81], v[150:151], v[228:229] op_sel_hi:[1,0]
	v_pk_mul_f32 v[68:69], v[148:149], v[228:229] op_sel_hi:[1,0]
	v_pk_mul_f32 v[130:131], v[146:147], v[228:229] op_sel_hi:[1,0]
	v_pk_mul_f32 v[134:135], v[144:145], v[228:229] op_sel_hi:[1,0]
	s_and_b64 s[10:11], vcc, s[0:1]
	s_and_saveexec_b64 s[0:1], s[10:11]
	s_cbranch_execz .LBB0_933
	s_waitcnt lgkmcnt(0)
	v_pk_fma_f32 v[84:85], v[80:81], v[166:167], v[170:171]
	v_pk_fma_f32 v[138:139], v[68:69], v[164:165], v[168:169]
	s_waitcnt lgkmcnt(2)
	v_pk_fma_f32 v[84:85], v[162:163], v[186:187], v[84:85]
	v_pk_fma_f32 v[138:139], v[160:161], v[184:185], v[138:139]
	v_pk_fma_f32 v[84:85], v[154:155], v[194:195], v[84:85]
	v_pk_fma_f32 v[138:139], v[152:153], v[192:193], v[138:139]
	v_mul_f32_e32 v146, 0xbfb8aa3b, v84
	v_mul_f32_e32 v144, 0xbfb8aa3b, v138
	v_mul_f32_e32 v145, 0xbfb8aa3b, v139
	v_mul_f32_e32 v147, 0xbfb8aa3b, v85
	v_exp_f32_e32 v144, v144
	v_exp_f32_e32 v145, v145
	v_exp_f32_e32 v146, v146
	v_exp_f32_e32 v147, v147
	v_add_f32_e32 v144, 1.0, v144
	v_add_f32_e32 v145, 1.0, v145
	v_add_f32_e32 v146, 1.0, v146
	v_add_f32_e32 v147, 1.0, v147
	v_rcp_f32_e32 v144, v144
	v_rcp_f32_e32 v145, v145
	v_rcp_f32_e32 v146, v146
	v_rcp_f32_e32 v147, v147
	s_waitcnt lgkmcnt(0)
	v_pk_fma_f32 v[72:73], v[130:131], v[178:179], v[182:183]
	v_pk_fma_f32 v[76:77], v[134:135], v[176:177], v[180:181]
	s_waitcnt lgkmcnt(0)
	v_pk_fma_f32 v[72:73], v[174:175], v[190:191], v[72:73]
	v_pk_fma_f32 v[76:77], v[172:173], v[188:189], v[76:77]
	v_pk_fma_f32 v[72:73], v[158:159], v[198:199], v[72:73]
	v_pk_fma_f32 v[76:77], v[156:157], v[196:197], v[76:77]
	v_pk_mul_f32 v[84:85], v[84:85], v[146:147]
	v_pk_mul_f32 v[138:139], v[138:139], v[144:145]
	v_pk_mul_f32 v[72:73], v[72:73], v[84:85]
	v_pk_mul_f32 v[76:77], v[76:77], v[138:139]
	s_nop 0
	v_cvt_pk_bf16_f32 v76, v76, v77
	v_cvt_pk_bf16_f32 v77, v72, v73
	v_mad_i64_i32 v[72:73], s[6:7], v200, s37, v[50:51]
	global_store_dwordx2 v[72:73], v[76:77], off
; __device__ __forceinline__ unsigned cvt_pk_bf16(float lo, float hi) { unsigned r; asm("v_cvt_pk_bf16_f32 %0, %1, %2" : "=v"(r) : "v"(lo), "v"(hi)); return r; }
;     __device__ __forceinline__ void operator()(const f32x4 (&acc)[2][2][4][2], const CU2& u, int wr, int wc, int fr_, int fq_) const {
;     ...
;             for (int j = 0; j < 8; ++j) {
;                 const f32x4 xg = acc[j >> 2][0][j & 3][n] * rsv[j], xv = acc[j >> 2][1][j & 3][n] * rsv[j];
;                 const f32x4 gc = gb + g2 * xg + g1 * pg1 + g0 * pg2, vc = vb + v2 * xv + v1 * pv1 + v0 * pv2;
;                 f32x4 sg;
; #pragma unroll
;                 for (int e = 0; e < 4; ++e) sg[e] = __builtin_amdgcn_rcpf(1.f + __expf(-gc[e]));
;                 const f32x4 o4 = gc * sg * vc;
;                 pg2 = pg1; pg1 = xg; pv2 = pv1; pv1 = xv;
;                 if (rb + j >= 2 && tb + j < T_) { u32x2 w; w.x = cvt_pk_bf16(o4[0], o4[1]); w.y = cvt_pk_bf16(o4[2], o4[3]); *(u32x2*)(act + (size_t)(tb + j) * FF_ + 128 * u.pn + cl + 4 * n) = w; }
;                 __builtin_amdgcn_sched_barrier(0);
.LBB0_933:
	s_or_b64 exec, exec, s[0:1]
	s_movk_i32 s0, 0x1fff
	v_cmp_lt_i32_e32 vcc, 0, v225
	v_cmp_gt_i32_e64 s[0:1], s0, v200
	v_pk_mul_f32 v[126:127], v[126:127], v[224:225] op_sel_hi:[1,0]
	v_pk_mul_f32 v[76:77], v[124:125], v[224:225] op_sel_hi:[1,0]
	v_pk_mul_f32 v[122:123], v[122:123], v[224:225] op_sel_hi:[1,0]
	v_pk_mul_f32 v[120:121], v[120:121], v[224:225] op_sel_hi:[1,0]
	s_and_b64 s[6:7], vcc, s[0:1]
	s_and_saveexec_b64 s[0:1], s[6:7]
	s_cbranch_execz .LBB0_935
	v_pk_fma_f32 v[124:125], v[126:127], v[166:167], v[170:171]
	v_pk_fma_f32 v[138:139], v[76:77], v[164:165], v[168:169]
	v_pk_fma_f32 v[124:125], v[80:81], v[162:163], v[124:125]
	v_pk_fma_f32 v[138:139], v[68:69], v[160:161], v[138:139]
	s_waitcnt lgkmcnt(0)
	v_pk_fma_f32 v[124:125], v[154:155], v[186:187], v[124:125]
	v_pk_fma_f32 v[138:139], v[152:153], v[184:185], v[138:139]
	v_mul_f32_e32 v146, 0xbfb8aa3b, v124
	v_mul_f32_e32 v144, 0xbfb8aa3b, v138
	v_mul_f32_e32 v145, 0xbfb8aa3b, v139
	v_mul_f32_e32 v147, 0xbfb8aa3b, v125
	v_exp_f32_e32 v144, v144
	v_exp_f32_e32 v145, v145
	v_exp_f32_e32 v146, v146
	v_exp_f32_e32 v147, v147
	v_add_f32_e32 v144, 1.0, v144
	v_add_f32_e32 v145, 1.0, v145
	v_add_f32_e32 v146, 1.0, v146
	v_add_f32_e32 v147, 1.0, v147
	v_rcp_f32_e32 v144, v144
	v_rcp_f32_e32 v145, v145
	v_rcp_f32_e32 v146, v146
	v_rcp_f32_e32 v147, v147
	v_pk_fma_f32 v[72:73], v[122:123], v[178:179], v[182:183]
	v_pk_fma_f32 v[84:85], v[120:121], v[176:177], v[180:181]
	v_pk_fma_f32 v[72:73], v[130:131], v[174:175], v[72:73]
	v_pk_fma_f32 v[84:85], v[134:135], v[172:173], v[84:85]
	v_pk_fma_f32 v[72:73], v[158:159], v[190:191], v[72:73]
	v_pk_fma_f32 v[84:85], v[156:157], v[188:189], v[84:85]
	v_pk_mul_f32 v[124:125], v[124:125], v[146:147]
	v_pk_mul_f32 v[138:139], v[138:139], v[144:145]
	v_pk_mul_f32 v[72:73], v[72:73], v[124:125]
	v_pk_mul_f32 v[84:85], v[84:85], v[138:139]
	s_nop 0
	v_cvt_pk_bf16_f32 v84, v84, v85
	v_cvt_pk_bf16_f32 v85, v72, v73
	v_mad_i64_i32 v[72:73], s[8:9], v223, s37, v[50:51]
	global_store_dwordx2 v[72:73], v[84:85], off
.LBB0_935:
	s_or_b64 exec, exec, s[0:1]
	v_cmp_lt_i32_e32 vcc, -1, v225
	v_cmp_gt_i32_e64 s[0:1], s89, v221
	v_pk_mul_f32 v[84:85], v[118:119], v[222:223] op_sel_hi:[1,0]
	v_pk_mul_f32 v[72:73], v[116:117], v[222:223] op_sel_hi:[1,0]
	v_pk_mul_f32 v[114:115], v[114:115], v[222:223] op_sel_hi:[1,0]
	v_pk_mul_f32 v[112:113], v[112:113], v[222:223] op_sel_hi:[1,0]
	s_and_b64 s[8:9], vcc, s[0:1]
	s_and_saveexec_b64 s[0:1], s[8:9]
	s_cbranch_execz .LBB0_937
	v_pk_fma_f32 v[116:117], v[114:115], v[178:179], v[182:183]
	v_pk_fma_f32 v[124:125], v[84:85], v[166:167], v[170:171]
	v_pk_fma_f32 v[116:117], v[122:123], v[174:175], v[116:117]
	v_pk_fma_f32 v[124:125], v[126:127], v[162:163], v[124:125]
	v_pk_fma_f32 v[116:117], v[130:131], v[158:159], v[116:117]
	v_pk_fma_f32 v[130:131], v[72:73], v[164:165], v[168:169]
	v_pk_fma_f32 v[80:81], v[80:81], v[154:155], v[124:125]
	v_pk_fma_f32 v[130:131], v[76:77], v[160:161], v[130:131]
	v_pk_fma_f32 v[118:119], v[112:113], v[176:177], v[180:181]
	v_pk_fma_f32 v[68:69], v[68:69], v[152:153], v[130:131]
	v_mul_f32_e32 v130, 0xbfb8aa3b, v80
	v_mul_f32_e32 v124, 0xbfb8aa3b, v68
	v_mul_f32_e32 v125, 0xbfb8aa3b, v69
	v_mul_f32_e32 v131, 0xbfb8aa3b, v81
	v_exp_f32_e32 v124, v124
	v_exp_f32_e32 v125, v125
	v_exp_f32_e32 v130, v130
	v_exp_f32_e32 v131, v131
	v_add_f32_e32 v124, 1.0, v124
	v_add_f32_e32 v125, 1.0, v125
	v_add_f32_e32 v130, 1.0, v130
	v_add_f32_e32 v131, 1.0, v131
	v_rcp_f32_e32 v124, v124
	v_rcp_f32_e32 v125, v125
	v_rcp_f32_e32 v130, v130
	v_rcp_f32_e32 v131, v131
	v_pk_fma_f32 v[118:119], v[120:121], v[172:173], v[118:119]
	v_pk_mul_f32 v[68:69], v[68:69], v[124:125]
	v_pk_fma_f32 v[118:119], v[134:135], v[156:157], v[118:119]
	v_pk_mul_f32 v[80:81], v[80:81], v[130:131]
	v_pk_mul_f32 v[68:69], v[118:119], v[68:69]
	v_pk_mul_f32 v[80:81], v[116:117], v[80:81]
	v_cvt_pk_bf16_f32 v68, v68, v69
	s_nop 0
	v_cvt_pk_bf16_f32 v69, v80, v81
	v_mad_i64_i32 v[80:81], s[12:13], v221, s37, v[50:51]
	global_store_dwordx2 v[80:81], v[68:69], off
.LBB0_937:
	s_or_b64 exec, exec, s[0:1]
	s_movk_i32 s0, 0x1ffd
	v_cmp_lt_i32_e32 vcc, -2, v225
	v_cmp_gt_i32_e64 s[0:1], s0, v200
	v_pk_mul_f32 v[80:81], v[110:111], v[220:221] op_sel_hi:[1,0]
	v_pk_mul_f32 v[68:69], v[108:109], v[220:221] op_sel_hi:[1,0]
	v_pk_mul_f32 v[106:107], v[106:107], v[220:221] op_sel_hi:[1,0]
	v_pk_mul_f32 v[104:105], v[104:105], v[220:221] op_sel_hi:[1,0]
	s_and_b64 s[12:13], vcc, s[0:1]
	s_and_saveexec_b64 s[0:1], s[12:13]
	s_cbranch_execz .LBB0_939
	v_pk_fma_f32 v[116:117], v[80:81], v[166:167], v[170:171]
	v_pk_fma_f32 v[118:119], v[68:69], v[164:165], v[168:169]
	v_pk_fma_f32 v[110:111], v[104:105], v[176:177], v[180:181]
	v_pk_fma_f32 v[116:117], v[84:85], v[162:163], v[116:117]
	v_pk_fma_f32 v[118:119], v[72:73], v[160:161], v[118:119]
	v_pk_fma_f32 v[110:111], v[112:113], v[172:173], v[110:111]
	v_pk_fma_f32 v[116:117], v[126:127], v[154:155], v[116:117]
	v_pk_fma_f32 v[76:77], v[76:77], v[152:153], v[118:119]
	v_pk_fma_f32 v[110:111], v[120:121], v[156:157], v[110:111]
	v_mul_f32_e32 v118, 0xbfb8aa3b, v76
	v_mul_f32_e32 v119, 0xbfb8aa3b, v77
	v_mul_f32_e32 v120, 0xbfb8aa3b, v116
	v_mul_f32_e32 v121, 0xbfb8aa3b, v117
	v_exp_f32_e32 v118, v118
	v_exp_f32_e32 v119, v119
	v_exp_f32_e32 v120, v120
	v_exp_f32_e32 v121, v121
	v_add_f32_e32 v118, 1.0, v118
	v_add_f32_e32 v119, 1.0, v119
	v_add_f32_e32 v120, 1.0, v120
	v_add_f32_e32 v121, 1.0, v121
	v_rcp_f32_e32 v118, v118
	v_rcp_f32_e32 v119, v119
	v_rcp_f32_e32 v120, v120
	v_rcp_f32_e32 v121, v121
	v_pk_fma_f32 v[108:109], v[106:107], v[178:179], v[182:183]
	v_pk_mul_f32 v[76:77], v[76:77], v[118:119]
	v_pk_fma_f32 v[108:109], v[114:115], v[174:175], v[108:109]
	v_pk_mul_f32 v[116:117], v[116:117], v[120:121]
	v_pk_fma_f32 v[108:109], v[122:123], v[158:159], v[108:109]
	v_pk_mul_f32 v[76:77], v[110:111], v[76:77]
	v_pk_mul_f32 v[108:109], v[108:109], v[116:117]
	v_cvt_pk_bf16_f32 v76, v76, v77
	s_nop 0
	v_cvt_pk_bf16_f32 v77, v108, v109
	v_mad_i64_i32 v[108:109], s[14:15], v219, s37, v[50:51]
	global_store_dwordx2 v[108:109], v[76:77], off
; __device__ __forceinline__ unsigned cvt_pk_bf16(float lo, float hi) { unsigned r; asm("v_cvt_pk_bf16_f32 %0, %1, %2" : "=v"(r) : "v"(lo), "v"(hi)); return r; }
;     __device__ __forceinline__ void operator()(const f32x4 (&acc)[2][2][4][2], const CU2& u, int wr, int wc, int fr_, int fq_) const {
;     ...
;             for (int j = 0; j < 8; ++j) {
;                 const f32x4 xg = acc[j >> 2][0][j & 3][n] * rsv[j], xv = acc[j >> 2][1][j & 3][n] * rsv[j];
;                 const f32x4 gc = gb + g2 * xg + g1 * pg1 + g0 * pg2, vc = vb + v2 * xv + v1 * pv1 + v0 * pv2;
;                 f32x4 sg;
; #pragma unroll
;                 for (int e = 0; e < 4; ++e) sg[e] = __builtin_amdgcn_rcpf(1.f + __expf(-gc[e]));
;                 const f32x4 o4 = gc * sg * vc;
;                 pg2 = pg1; pg1 = xg; pv2 = pv1; pv1 = xv;
;                 if (rb + j >= 2 && tb + j < T_) { u32x2 w; w.x = cvt_pk_bf16(o4[0], o4[1]); w.y = cvt_pk_bf16(o4[2], o4[3]); *(u32x2*)(act + (size_t)(tb + j) * FF_ + 128 * u.pn + cl + 4 * n) = w; }
;                 __builtin_amdgcn_sched_barrier(0);
.LBB0_939:
	s_or_b64 exec, exec, s[0:1]
	s_movk_i32 s0, 0x1ffc
	v_cmp_lt_i32_e32 vcc, -3, v225
	v_cmp_gt_i32_e64 s[0:1], s0, v200
	v_pk_mul_f32 v[102:103], v[102:103], v[218:219] op_sel_hi:[1,0]
	v_pk_mul_f32 v[76:77], v[100:101], v[218:219] op_sel_hi:[1,0]
	v_pk_mul_f32 v[98:99], v[98:99], v[218:219] op_sel_hi:[1,0]
	v_pk_mul_f32 v[96:97], v[96:97], v[218:219] op_sel_hi:[1,0]
	s_and_b64 s[14:15], vcc, s[0:1]
	s_and_saveexec_b64 s[0:1], s[14:15]
	s_cbranch_execz .LBB0_941
	v_pk_fma_f32 v[108:109], v[96:97], v[176:177], v[180:181]
	v_pk_fma_f32 v[110:111], v[102:103], v[166:167], v[170:171]
	v_pk_fma_f32 v[108:109], v[104:105], v[172:173], v[108:109]
	v_pk_fma_f32 v[110:111], v[80:81], v[162:163], v[110:111]
	v_pk_fma_f32 v[108:109], v[112:113], v[156:157], v[108:109]
	v_pk_fma_f32 v[112:113], v[76:77], v[164:165], v[168:169]
	v_pk_fma_f32 v[84:85], v[84:85], v[154:155], v[110:111]
	v_pk_fma_f32 v[112:113], v[68:69], v[160:161], v[112:113]
	v_pk_fma_f32 v[100:101], v[98:99], v[178:179], v[182:183]
	v_pk_fma_f32 v[72:73], v[72:73], v[152:153], v[112:113]
	v_mul_f32_e32 v112, 0xbfb8aa3b, v84
	v_mul_f32_e32 v110, 0xbfb8aa3b, v72
	v_mul_f32_e32 v111, 0xbfb8aa3b, v73
	v_mul_f32_e32 v113, 0xbfb8aa3b, v85
	v_exp_f32_e32 v110, v110
	v_exp_f32_e32 v111, v111
	v_exp_f32_e32 v112, v112
	v_exp_f32_e32 v113, v113
	v_add_f32_e32 v110, 1.0, v110
	v_add_f32_e32 v111, 1.0, v111
	v_add_f32_e32 v112, 1.0, v112
	v_add_f32_e32 v113, 1.0, v113
	v_rcp_f32_e32 v110, v110
	v_rcp_f32_e32 v111, v111
	v_rcp_f32_e32 v112, v112
	v_rcp_f32_e32 v113, v113
	v_pk_fma_f32 v[100:101], v[106:107], v[174:175], v[100:101]
	v_pk_mul_f32 v[72:73], v[72:73], v[110:111]
	v_pk_fma_f32 v[100:101], v[114:115], v[158:159], v[100:101]
	v_pk_mul_f32 v[84:85], v[84:85], v[112:113]
	v_pk_mul_f32 v[72:73], v[108:109], v[72:73]
	v_pk_mul_f32 v[84:85], v[100:101], v[84:85]
	v_cvt_pk_bf16_f32 v72, v72, v73
	s_nop 0
	v_cvt_pk_bf16_f32 v73, v84, v85
	v_mad_i64_i32 v[84:85], s[26:27], v217, s37, v[50:51]
	global_store_dwordx2 v[84:85], v[72:73], off
.LBB0_941:
	s_or_b64 exec, exec, s[0:1]
	s_movk_i32 s0, 0x1ffb
	v_cmp_lt_i32_e32 vcc, -4, v225
	v_cmp_gt_i32_e64 s[0:1], s0, v200
	v_pk_mul_f32 v[94:95], v[94:95], v[216:217] op_sel_hi:[1,0]
	v_pk_mul_f32 v[92:93], v[92:93], v[216:217] op_sel_hi:[1,0]
	v_pk_mul_f32 v[72:73], v[90:91], v[216:217] op_sel_hi:[1,0]
	v_pk_mul_f32 v[84:85], v[88:89], v[216:217] op_sel_hi:[1,0]
	s_and_b64 s[26:27], vcc, s[0:1]
	s_and_saveexec_b64 s[0:1], s[26:27]
	s_cbranch_execz .LBB0_943
	v_pk_fma_f32 v[90:91], v[84:85], v[176:177], v[180:181]
	v_pk_fma_f32 v[100:101], v[94:95], v[166:167], v[170:171]
	v_pk_fma_f32 v[90:91], v[96:97], v[172:173], v[90:91]
	v_pk_fma_f32 v[100:101], v[102:103], v[162:163], v[100:101]
	v_pk_fma_f32 v[90:91], v[104:105], v[156:157], v[90:91]
	v_pk_fma_f32 v[104:105], v[92:93], v[164:165], v[168:169]
	v_pk_fma_f32 v[80:81], v[80:81], v[154:155], v[100:101]
	v_pk_fma_f32 v[104:105], v[76:77], v[160:161], v[104:105]
	v_pk_fma_f32 v[88:89], v[72:73], v[178:179], v[182:183]
	v_pk_fma_f32 v[68:69], v[68:69], v[152:153], v[104:105]
	v_mul_f32_e32 v104, 0xbfb8aa3b, v80
	v_mul_f32_e32 v100, 0xbfb8aa3b, v68
	v_mul_f32_e32 v101, 0xbfb8aa3b, v69
	v_mul_f32_e32 v105, 0xbfb8aa3b, v81
	v_exp_f32_e32 v100, v100
	v_exp_f32_e32 v101, v101
	v_exp_f32_e32 v104, v104
	v_exp_f32_e32 v105, v105
	v_add_f32_e32 v100, 1.0, v100
	v_add_f32_e32 v101, 1.0, v101
	v_add_f32_e32 v104, 1.0, v104
	v_add_f32_e32 v105, 1.0, v105
	v_rcp_f32_e32 v100, v100
	v_rcp_f32_e32 v101, v101
	v_rcp_f32_e32 v104, v104
	v_rcp_f32_e32 v105, v105
	v_pk_fma_f32 v[88:89], v[98:99], v[174:175], v[88:89]
	v_pk_mul_f32 v[68:69], v[68:69], v[100:101]
	v_pk_fma_f32 v[88:89], v[106:107], v[158:159], v[88:89]
	v_pk_mul_f32 v[80:81], v[80:81], v[104:105]
	v_pk_mul_f32 v[68:69], v[90:91], v[68:69]
	v_pk_mul_f32 v[80:81], v[88:89], v[80:81]
	v_cvt_pk_bf16_f32 v68, v68, v69
	s_nop 0
	v_cvt_pk_bf16_f32 v69, v80, v81
	v_mad_i64_i32 v[80:81], s[28:29], v246, s37, v[50:51]
	global_store_dwordx2 v[80:81], v[68:69], off
.LBB0_943:
	s_or_b64 exec, exec, s[0:1]
	s_movk_i32 s0, 0x1ffa
	v_mov_b32_e32 v233, v232
	v_cmp_lt_i32_e32 vcc, -5, v225
	v_cmp_gt_i32_e64 s[0:1], s0, v200
	v_pk_mul_f32 v[68:69], v[86:87], v[232:233]
	s_and_b64 s[28:29], vcc, s[0:1]
	s_and_saveexec_b64 s[0:1], s[28:29]
	s_cbranch_execz .LBB0_945
	v_pk_fma_f32 v[88:89], v[142:143], v[166:167], v[170:171]
	v_pk_fma_f32 v[90:91], v[140:141], v[164:165], v[168:169]
	v_pk_fma_f32 v[86:87], v[132:133], v[176:177], v[180:181]
	v_pk_fma_f32 v[88:89], v[94:95], v[162:163], v[88:89]
	v_pk_fma_f32 v[90:91], v[92:93], v[160:161], v[90:91]
	v_pk_fma_f32 v[86:87], v[84:85], v[172:173], v[86:87]
	v_pk_fma_f32 v[88:89], v[102:103], v[154:155], v[88:89]
	v_pk_fma_f32 v[76:77], v[76:77], v[152:153], v[90:91]
	v_pk_fma_f32 v[86:87], v[96:97], v[156:157], v[86:87]
	v_mul_f32_e32 v90, 0xbfb8aa3b, v76
	v_mul_f32_e32 v91, 0xbfb8aa3b, v77
	v_mul_f32_e32 v96, 0xbfb8aa3b, v88
	v_mul_f32_e32 v97, 0xbfb8aa3b, v89
	v_exp_f32_e32 v90, v90
	v_exp_f32_e32 v91, v91
	v_exp_f32_e32 v96, v96
	v_exp_f32_e32 v97, v97
	v_add_f32_e32 v90, 1.0, v90
	v_add_f32_e32 v91, 1.0, v91
	v_add_f32_e32 v96, 1.0, v96
	v_add_f32_e32 v97, 1.0, v97
	v_rcp_f32_e32 v90, v90
	v_rcp_f32_e32 v91, v91
	v_rcp_f32_e32 v96, v96
	v_rcp_f32_e32 v97, v97
	v_pk_fma_f32 v[80:81], v[68:69], v[178:179], v[182:183]
	v_pk_mul_f32 v[76:77], v[76:77], v[90:91]
	v_pk_fma_f32 v[80:81], v[72:73], v[174:175], v[80:81]
	v_pk_mul_f32 v[88:89], v[88:89], v[96:97]
	v_pk_fma_f32 v[80:81], v[98:99], v[158:159], v[80:81]
	v_pk_mul_f32 v[76:77], v[86:87], v[76:77]
	v_pk_mul_f32 v[80:81], v[80:81], v[88:89]
	v_cvt_pk_bf16_f32 v76, v76, v77
	s_nop 0
	v_cvt_pk_bf16_f32 v77, v80, v81
	v_mad_i64_i32 v[80:81], s[30:31], v245, s37, v[50:51]
	global_store_dwordx2 v[80:81], v[76:77], off
; #define LAS __attribute__((address_space(3)))
;     __device__ __forceinline__ void operator()(const f32x4 (&acc)[2][2][4][2], const CU2& u, int wr, int wc, int fr_, int fq_) const {
;     ...
;         for (int n = 0; n < 2; ++n) {
;             const float* wp = cw + 128 * u.pn + cl + 4 * n; const float* bp = cb + 128 * u.pn + cl + 4 * n;
;             const f32x4 g0 = *(const f32x4*)wp, g1 = *(const f32x4*)(wp + 2 * FF_), g2 = *(const f32x4*)(wp + 4 * FF_), gb = *(const f32x4*)bp;
;             const f32x4 v0 = *(const f32x4*)(wp + FF_), v1 = *(const f32x4*)(wp + 3 * FF_), v2 = *(const f32x4*)(wp + 5 * FF_), vb = *(const f32x4*)(bp + FF_);
;             f32x4 pg2 = acc[1][0][2][n] * rsv[6], pg1 = acc[1][0][3][n] * rsv[7], pv2 = acc[1][1][2][n] * rsv[6], pv1 = acc[1][1][3][n] * rsv[7];
; #pragma unroll
;             for (int e = 0; e < 4; ++e) {
;                 pg2[e] = __int_as_float(__builtin_amdgcn_mov_dpp(__float_as_int(pg2[e]), 0x111, 0xF, 0xF, true)); pg1[e] = __int_as_float(__builtin_amdgcn_mov_dpp(__float_as_int(pg1[e]), 0x111, 0xF, 0xF, true));
;                 pv2[e] = __int_as_float(__builtin_amdgcn_mov_dpp(__float_as_int(pv2[e]), 0x111, 0xF, 0xF, true)); pv1[e] = __int_as_float(__builtin_amdgcn_mov_dpp(__float_as_int(pv1[e]), 0x111, 0xF, 0xF, true));
;             }
;             if (fr == 0 && wr == 1) { pg2 = *(const LAS f32x4*)(hal + cl + 4 * n); pg1 = *(const LAS f32x4*)(hal + 256 + cl + 4 * n); pv2 = *(const LAS f32x4*)(hal + 128 + cl + 4 * n); pv1 = *(const LAS f32x4*)(hal + 384 + cl + 4 * n); }
; #pragma unroll
;             for (int j = 0; j < 8; ++j) {
;                 const f32x4 xg = acc[j >> 2][0][j & 3][n] * rsv[j], xv = acc[j >> 2][1][j & 3][n] * rsv[j];
;                 const f32x4 gc = gb + g2 * xg + g1 * pg1 + g0 * pg2, vc = vb + v2 * xv + v1 * pv1 + v0 * pv2;
;                 f32x4 sg;
; #pragma unroll
;                 for (int e = 0; e < 4; ++e) sg[e] = __builtin_amdgcn_rcpf(1.f + __expf(-gc[e]));
;                 const f32x4 o4 = gc * sg * vc;
;                 pg2 = pg1; pg1 = xg; pv2 = pv1; pv1 = xv;
;                 if (rb + j >= 2 && tb + j < T_) { u32x2 w; w.x = cvt_pk_bf16(o4[0], o4[1]); w.y = cvt_pk_bf16(o4[2], o4[3]); *(u32x2*)(act + (size_t)(tb + j) * FF_ + 128 * u.pn + cl + 4 * n) = w; }
.LBB0_945:
	s_or_b64 exec, exec, s[0:1]
	s_movk_i32 s0, 0x1ff9
	v_cmp_lt_i32_e32 vcc, -6, v225
	v_cmp_gt_i32_e64 s[0:1], s0, v200
	s_and_b64 s[0:1], vcc, s[0:1]
	s_and_saveexec_b64 s[30:31], s[0:1]
	s_cbranch_execz .LBB0_947
	v_mov_b32_e32 v231, v230
	v_pk_mul_f32 v[76:77], v[78:79], v[230:231]
	v_pk_fma_f32 v[78:79], v[136:137], v[176:177], v[180:181]
	v_pk_fma_f32 v[76:77], v[76:77], v[178:179], v[182:183]
	v_pk_fma_f32 v[80:81], v[128:129], v[164:165], v[168:169]
	v_pk_fma_f32 v[68:69], v[68:69], v[174:175], v[76:77]
	v_pk_fma_f32 v[76:77], v[132:133], v[172:173], v[78:79]
	v_pk_mul_f32 v[78:79], v[82:83], v[230:231]
	v_pk_fma_f32 v[80:81], v[140:141], v[160:161], v[80:81]
	v_pk_fma_f32 v[78:79], v[78:79], v[166:167], v[170:171]
	v_pk_fma_f32 v[80:81], v[92:93], v[152:153], v[80:81]
	v_pk_fma_f32 v[78:79], v[142:143], v[162:163], v[78:79]
	v_mul_f32_e32 v82, 0xbfb8aa3b, v80
	v_pk_fma_f32 v[78:79], v[94:95], v[154:155], v[78:79]
	v_mul_f32_e32 v83, 0xbfb8aa3b, v81
	v_mul_f32_e32 v86, 0xbfb8aa3b, v78
	v_mul_f32_e32 v87, 0xbfb8aa3b, v79
	v_exp_f32_e32 v82, v82
	v_exp_f32_e32 v83, v83
	v_exp_f32_e32 v86, v86
	v_exp_f32_e32 v87, v87
	v_add_f32_e32 v82, 1.0, v82
	v_add_f32_e32 v83, 1.0, v83
	v_add_f32_e32 v86, 1.0, v86
	v_add_f32_e32 v87, 1.0, v87
	v_rcp_f32_e32 v82, v82
	v_rcp_f32_e32 v86, v86
	v_rcp_f32_e32 v87, v87
	v_rcp_f32_e32 v83, v83
	v_pk_fma_f32 v[68:69], v[72:73], v[158:159], v[68:69]
	v_pk_fma_f32 v[72:73], v[84:85], v[156:157], v[76:77]
	v_pk_mul_f32 v[76:77], v[78:79], v[86:87]
	v_pk_mul_f32 v[78:79], v[80:81], v[82:83]
	v_pk_mul_f32 v[68:69], v[68:69], v[76:77]
	v_pk_mul_f32 v[72:73], v[72:73], v[78:79]
	s_nop 0
	v_cvt_pk_bf16_f32 v72, v72, v73
	v_cvt_pk_bf16_f32 v73, v68, v69
	v_mad_i64_i32 v[68:69], vcc, v244, s37, v[50:51]
	global_store_dwordx2 v[68:69], v[72:73], off
.LBB0_947:
	s_or_b64 exec, exec, s[30:31]
	v_add_co_u32_e32 v68, vcc, 0xb000, v54
	ds_read_b128 v[76:79], v237 offset:16
	s_nop 0
	v_addc_co_u32_e32 v69, vcc, 0, v55, vcc
	v_add_co_u32_e32 v72, vcc, 0x16000, v54
	v_mov_b32_e32 v233, v232
	s_nop 0
	v_addc_co_u32_e32 v73, vcc, 0, v55, vcc
	ds_read_b128 v[84:87], v237 offset:528
	ds_read_b128 v[88:91], v237 offset:1040
	ds_read_b128 v[92:95], v237 offset:1552
	v_add_co_u32_e32 v68, vcc, 0x5000, v54
	v_mov_b32_e32 v231, v230
	s_nop 0
	v_addc_co_u32_e32 v69, vcc, 0, v55, vcc
	v_add_co_u32_e32 v54, vcc, 0x1b000, v54
	ds_read_b128 v[80:83], v237 offset:2064
	ds_read_b128 v[96:99], v237 offset:2576
	v_addc_co_u32_e32 v55, vcc, 0, v55, vcc
	v_add_co_u32_e32 v44, vcc, 0x5000, v44
	ds_read_b128 v[100:103], v237 offset:3088
	s_nop 0
	v_addc_co_u32_e32 v45, vcc, 0, v45, vcc
	ds_read_b128 v[104:107], v237 offset:3600
	v_pk_mul_f32 v[64:65], v[74:75], v[232:233]
	v_pk_mul_f32 v[108:109], v[70:71], v[230:231]
	v_pk_mul_f32 v[110:111], v[56:57], v[232:233]
	v_pk_mul_f32 v[112:113], v[46:47], v[230:231]
	v_mov_b32_dpp v68, v48 row_shr:1 row_mask:0xf bank_mask:0xf bound_ctrl:1
	v_mov_b32_dpp v44, v52 row_shr:1 row_mask:0xf bank_mask:0xf bound_ctrl:1
	v_mov_b32_dpp v72, v62 row_shr:1 row_mask:0xf bank_mask:0xf bound_ctrl:1
	v_mov_b32_dpp v54, v66 row_shr:1 row_mask:0xf bank_mask:0xf bound_ctrl:1
	v_mov_b32_dpp v69, v49 row_shr:1 row_mask:0xf bank_mask:0xf bound_ctrl:1
	v_mov_b32_dpp v45, v53 row_shr:1 row_mask:0xf bank_mask:0xf bound_ctrl:1
	v_mov_b32_dpp v73, v63 row_shr:1 row_mask:0xf bank_mask:0xf bound_ctrl:1
	v_mov_b32_dpp v55, v67 row_shr:1 row_mask:0xf bank_mask:0xf bound_ctrl:1
	v_mov_b32_dpp v70, v64 row_shr:1 row_mask:0xf bank_mask:0xf bound_ctrl:1
	v_mov_b32_dpp v46, v108 row_shr:1 row_mask:0xf bank_mask:0xf bound_ctrl:1
	v_mov_b32_dpp v74, v110 row_shr:1 row_mask:0xf bank_mask:0xf bound_ctrl:1
	v_mov_b32_dpp v56, v112 row_shr:1 row_mask:0xf bank_mask:0xf bound_ctrl:1
	v_mov_b32_dpp v71, v65 row_shr:1 row_mask:0xf bank_mask:0xf bound_ctrl:1
	v_mov_b32_dpp v47, v109 row_shr:1 row_mask:0xf bank_mask:0xf bound_ctrl:1
	v_mov_b32_dpp v75, v111 row_shr:1 row_mask:0xf bank_mask:0xf bound_ctrl:1
	v_mov_b32_dpp v57, v113 row_shr:1 row_mask:0xf bank_mask:0xf bound_ctrl:1
	s_and_saveexec_b64 s[30:31], s[4:5]
	s_cbranch_execz .LBB0_949
	v_readlane_b32 s4, v255, 38
	s_nop 1
	v_lshl_add_u32 v54, v226, 2, s4
	ds_read_b128 v[68:71], v54 offset:16
	ds_read_b128 v[72:75], v54 offset:528
	ds_read_b128 v[44:47], v54 offset:1040
	ds_read_b128 v[54:57], v54 offset:1552
.LBB0_949:
	s_or_b64 exec, exec, s[30:31]
	v_mov_b32_e32 v229, v228
	v_mov_b32_e32 v114, v228
	v_mov_b32_e32 v115, v228
	v_pk_mul_f32 v[60:61], v[60:61], v[114:115]
	v_pk_mul_f32 v[58:59], v[58:59], v[228:229]
	v_pk_mul_f32 v[42:43], v[42:43], v[114:115]
	v_pk_mul_f32 v[40:41], v[40:41], v[228:229]
	s_and_saveexec_b64 s[4:5], s[10:11]
	s_cbranch_execz .LBB0_951
	s_waitcnt lgkmcnt(0)
	v_pk_fma_f32 v[114:115], v[42:43], v[102:103], v[106:107]
	v_pk_fma_f32 v[116:117], v[40:41], v[100:101], v[104:105]
	s_waitcnt lgkmcnt(0)
	v_pk_fma_f32 v[114:115], v[98:99], v[56:57], v[114:115]
	v_pk_fma_f32 v[116:117], v[96:97], v[54:55], v[116:117]
	v_pk_fma_f32 v[74:75], v[82:83], v[74:75], v[114:115]
	v_pk_fma_f32 v[72:73], v[80:81], v[72:73], v[116:117]
	v_pk_fma_f32 v[114:115], v[60:61], v[90:91], v[94:95]
	v_pk_fma_f32 v[116:117], v[58:59], v[88:89], v[92:93]
	v_pk_fma_f32 v[114:115], v[86:87], v[46:47], v[114:115]
	v_pk_fma_f32 v[116:117], v[84:85], v[44:45], v[116:117]
	v_pk_fma_f32 v[70:71], v[78:79], v[70:71], v[114:115]
	v_pk_fma_f32 v[68:69], v[76:77], v[68:69], v[116:117]
	v_mul_f32_e32 v116, 0xbfb8aa3b, v70
	v_mul_f32_e32 v114, 0xbfb8aa3b, v68
	v_mul_f32_e32 v115, 0xbfb8aa3b, v69
	v_mul_f32_e32 v117, 0xbfb8aa3b, v71
	v_exp_f32_e32 v114, v114
	v_exp_f32_e32 v115, v115
	v_exp_f32_e32 v116, v116
	v_exp_f32_e32 v117, v117
	v_add_f32_e32 v114, 1.0, v114
	v_add_f32_e32 v115, 1.0, v115
	v_add_f32_e32 v116, 1.0, v116
	v_add_f32_e32 v117, 1.0, v117
	v_rcp_f32_e32 v114, v114
	v_rcp_f32_e32 v115, v115
	v_rcp_f32_e32 v116, v116
	v_rcp_f32_e32 v117, v117
	v_pk_mul_f32 v[68:69], v[68:69], v[114:115]
	s_nop 0
	v_pk_mul_f32 v[68:69], v[72:73], v[68:69]
	v_pk_mul_f32 v[70:71], v[70:71], v[116:117]
	v_cvt_pk_bf16_f32 v68, v68, v69
	s_nop 0
	v_pk_mul_f32 v[70:71], v[74:75], v[70:71]
	s_nop 0
	v_cvt_pk_bf16_f32 v69, v70, v71
	v_mad_i64_i32 v[70:71], s[10:11], v200, s37, v[50:51]
	global_store_dwordx2 v[70:71], v[68:69], off offset:8
; __device__ __forceinline__ unsigned cvt_pk_bf16(float lo, float hi) { unsigned r; asm("v_cvt_pk_bf16_f32 %0, %1, %2" : "=v"(r) : "v"(lo), "v"(hi)); return r; }
;     __device__ __forceinline__ void operator()(const f32x4 (&acc)[2][2][4][2], const CU2& u, int wr, int wc, int fr_, int fq_) const {
;     ...
;             for (int j = 0; j < 8; ++j) {
;                 const f32x4 xg = acc[j >> 2][0][j & 3][n] * rsv[j], xv = acc[j >> 2][1][j & 3][n] * rsv[j];
;                 const f32x4 gc = gb + g2 * xg + g1 * pg1 + g0 * pg2, vc = vb + v2 * xv + v1 * pv1 + v0 * pv2;
;                 f32x4 sg;
; #pragma unroll
;                 for (int e = 0; e < 4; ++e) sg[e] = __builtin_amdgcn_rcpf(1.f + __expf(-gc[e]));
;                 const f32x4 o4 = gc * sg * vc;
;                 pg2 = pg1; pg1 = xg; pv2 = pv1; pv1 = xv;
;                 if (rb + j >= 2 && tb + j < T_) { u32x2 w; w.x = cvt_pk_bf16(o4[0], o4[1]); w.y = cvt_pk_bf16(o4[2], o4[3]); *(u32x2*)(act + (size_t)(tb + j) * FF_ + 128 * u.pn + cl + 4 * n) = w; }
;                 __builtin_amdgcn_sched_barrier(0);
.LBB0_951:
	s_or_b64 exec, exec, s[4:5]
	v_mov_b32_e32 v225, v224
	s_waitcnt lgkmcnt(0)
	v_mov_b32_e32 v68, v224
	v_mov_b32_e32 v69, v224
	v_pk_mul_f32 v[38:39], v[38:39], v[68:69]
	v_pk_mul_f32 v[36:37], v[36:37], v[224:225]
	v_pk_mul_f32 v[34:35], v[34:35], v[68:69]
	v_pk_mul_f32 v[32:33], v[32:33], v[224:225]
	s_and_saveexec_b64 s[4:5], s[6:7]
	s_cbranch_execz .LBB0_953
	v_pk_fma_f32 v[68:69], v[34:35], v[102:103], v[106:107]
	v_pk_fma_f32 v[70:71], v[32:33], v[100:101], v[104:105]
	v_pk_fma_f32 v[68:69], v[42:43], v[98:99], v[68:69]
	v_pk_fma_f32 v[70:71], v[40:41], v[96:97], v[70:71]
	v_pk_fma_f32 v[56:57], v[82:83], v[56:57], v[68:69]
	v_pk_fma_f32 v[54:55], v[80:81], v[54:55], v[70:71]
	v_pk_fma_f32 v[68:69], v[38:39], v[90:91], v[94:95]
	v_pk_fma_f32 v[70:71], v[36:37], v[88:89], v[92:93]
	v_pk_fma_f32 v[68:69], v[60:61], v[86:87], v[68:69]
	v_pk_fma_f32 v[70:71], v[58:59], v[84:85], v[70:71]
	v_pk_fma_f32 v[46:47], v[78:79], v[46:47], v[68:69]
	v_pk_fma_f32 v[44:45], v[76:77], v[44:45], v[70:71]
	v_mul_f32_e32 v70, 0xbfb8aa3b, v46
	v_mul_f32_e32 v68, 0xbfb8aa3b, v44
	v_mul_f32_e32 v69, 0xbfb8aa3b, v45
	v_mul_f32_e32 v71, 0xbfb8aa3b, v47
	v_exp_f32_e32 v68, v68
	v_exp_f32_e32 v69, v69
	v_exp_f32_e32 v70, v70
	v_exp_f32_e32 v71, v71
	v_add_f32_e32 v68, 1.0, v68
	v_add_f32_e32 v69, 1.0, v69
	v_add_f32_e32 v70, 1.0, v70
	v_add_f32_e32 v71, 1.0, v71
	v_rcp_f32_e32 v68, v68
	v_rcp_f32_e32 v69, v69
	v_rcp_f32_e32 v70, v70
	v_rcp_f32_e32 v71, v71
	v_pk_mul_f32 v[44:45], v[44:45], v[68:69]
	s_nop 0
	v_pk_mul_f32 v[44:45], v[54:55], v[44:45]
	v_pk_mul_f32 v[46:47], v[46:47], v[70:71]
	v_cvt_pk_bf16_f32 v44, v44, v45
	s_nop 0
	v_pk_mul_f32 v[46:47], v[56:57], v[46:47]
	s_nop 0
	v_cvt_pk_bf16_f32 v45, v46, v47
	v_mad_i64_i32 v[46:47], s[6:7], v223, s37, v[50:51]
	global_store_dwordx2 v[46:47], v[44:45], off offset:8
.LBB0_953:
	s_or_b64 exec, exec, s[4:5]
	v_mov_b32_e32 v223, v222
	v_mov_b32_e32 v44, v222
	v_mov_b32_e32 v45, v222
	v_pk_mul_f32 v[30:31], v[30:31], v[44:45]
	v_pk_mul_f32 v[28:29], v[28:29], v[222:223]
	v_pk_mul_f32 v[26:27], v[26:27], v[44:45]
	v_pk_mul_f32 v[24:25], v[24:25], v[222:223]
	s_and_saveexec_b64 s[4:5], s[8:9]
	s_cbranch_execz .LBB0_955
	v_pk_fma_f32 v[44:45], v[26:27], v[102:103], v[106:107]
	v_pk_fma_f32 v[46:47], v[24:25], v[100:101], v[104:105]
	v_pk_fma_f32 v[44:45], v[34:35], v[98:99], v[44:45]
	v_pk_fma_f32 v[46:47], v[32:33], v[96:97], v[46:47]
	v_pk_fma_f32 v[42:43], v[42:43], v[82:83], v[44:45]
	v_pk_fma_f32 v[40:41], v[40:41], v[80:81], v[46:47]
	v_pk_fma_f32 v[44:45], v[30:31], v[90:91], v[94:95]
	v_pk_fma_f32 v[46:47], v[28:29], v[88:89], v[92:93]
	v_pk_fma_f32 v[44:45], v[38:39], v[86:87], v[44:45]
	v_pk_fma_f32 v[46:47], v[36:37], v[84:85], v[46:47]
	v_pk_fma_f32 v[44:45], v[60:61], v[78:79], v[44:45]
	v_pk_fma_f32 v[46:47], v[58:59], v[76:77], v[46:47]
	v_mul_f32_e32 v56, 0xbfb8aa3b, v44
	v_mul_f32_e32 v54, 0xbfb8aa3b, v46
	v_mul_f32_e32 v55, 0xbfb8aa3b, v47
	v_mul_f32_e32 v57, 0xbfb8aa3b, v45
	v_exp_f32_e32 v54, v54
	v_exp_f32_e32 v55, v55
	v_exp_f32_e32 v56, v56
	v_exp_f32_e32 v57, v57
	v_add_f32_e32 v54, 1.0, v54
	v_add_f32_e32 v55, 1.0, v55
	v_add_f32_e32 v56, 1.0, v56
	v_add_f32_e32 v57, 1.0, v57
	v_rcp_f32_e32 v54, v54
	v_rcp_f32_e32 v55, v55
	v_rcp_f32_e32 v56, v56
	v_rcp_f32_e32 v57, v57
	v_pk_mul_f32 v[46:47], v[46:47], v[54:55]
	s_nop 0
	v_pk_mul_f32 v[40:41], v[40:41], v[46:47]
	v_pk_mul_f32 v[44:45], v[44:45], v[56:57]
	v_cvt_pk_bf16_f32 v40, v40, v41
	s_nop 0
	v_pk_mul_f32 v[42:43], v[42:43], v[44:45]
	s_nop 0
	v_cvt_pk_bf16_f32 v41, v42, v43
	v_mad_i64_i32 v[42:43], s[6:7], v221, s37, v[50:51]
	global_store_dwordx2 v[42:43], v[40:41], off offset:8
.LBB0_955:
	s_or_b64 exec, exec, s[4:5]
	v_mov_b32_e32 v221, v220
	v_mov_b32_e32 v40, v220
	v_mov_b32_e32 v41, v220
	v_pk_mul_f32 v[22:23], v[22:23], v[40:41]
	v_pk_mul_f32 v[20:21], v[20:21], v[220:221]
	v_pk_mul_f32 v[18:19], v[18:19], v[40:41]
	v_pk_mul_f32 v[16:17], v[16:17], v[220:221]
	s_and_saveexec_b64 s[4:5], s[12:13]
	s_cbranch_execz .LBB0_957
	v_pk_fma_f32 v[40:41], v[18:19], v[102:103], v[106:107]
	v_pk_fma_f32 v[42:43], v[16:17], v[100:101], v[104:105]
	v_pk_fma_f32 v[40:41], v[26:27], v[98:99], v[40:41]
	v_pk_fma_f32 v[42:43], v[24:25], v[96:97], v[42:43]
	v_pk_fma_f32 v[34:35], v[34:35], v[82:83], v[40:41]
	v_pk_fma_f32 v[32:33], v[32:33], v[80:81], v[42:43]
	v_pk_fma_f32 v[40:41], v[22:23], v[90:91], v[94:95]
	v_pk_fma_f32 v[42:43], v[20:21], v[88:89], v[92:93]
	v_pk_fma_f32 v[40:41], v[30:31], v[86:87], v[40:41]
	v_pk_fma_f32 v[42:43], v[28:29], v[84:85], v[42:43]
	v_pk_fma_f32 v[38:39], v[38:39], v[78:79], v[40:41]
	v_pk_fma_f32 v[36:37], v[36:37], v[76:77], v[42:43]
	v_mul_f32_e32 v42, 0xbfb8aa3b, v38
	v_mul_f32_e32 v40, 0xbfb8aa3b, v36
	v_mul_f32_e32 v41, 0xbfb8aa3b, v37
	v_mul_f32_e32 v43, 0xbfb8aa3b, v39
	v_exp_f32_e32 v40, v40
	v_exp_f32_e32 v41, v41
	v_exp_f32_e32 v42, v42
	v_exp_f32_e32 v43, v43
	v_add_f32_e32 v40, 1.0, v40
	v_add_f32_e32 v41, 1.0, v41
	v_add_f32_e32 v42, 1.0, v42
	v_add_f32_e32 v43, 1.0, v43
	v_rcp_f32_e32 v40, v40
	v_rcp_f32_e32 v41, v41
	v_rcp_f32_e32 v42, v42
	v_rcp_f32_e32 v43, v43
	v_pk_mul_f32 v[36:37], v[36:37], v[40:41]
	s_nop 0
	v_pk_mul_f32 v[32:33], v[32:33], v[36:37]
	v_pk_mul_f32 v[38:39], v[38:39], v[42:43]
	v_cvt_pk_bf16_f32 v32, v32, v33
	s_nop 0
	v_pk_mul_f32 v[34:35], v[34:35], v[38:39]
	s_nop 0
	v_cvt_pk_bf16_f32 v33, v34, v35
	v_mad_i64_i32 v[34:35], s[6:7], v219, s37, v[50:51]
	global_store_dwordx2 v[34:35], v[32:33], off offset:8
; __device__ __forceinline__ unsigned cvt_pk_bf16(float lo, float hi) { unsigned r; asm("v_cvt_pk_bf16_f32 %0, %1, %2" : "=v"(r) : "v"(lo), "v"(hi)); return r; }
;     __device__ __forceinline__ void operator()(const f32x4 (&acc)[2][2][4][2], const CU2& u, int wr, int wc, int fr_, int fq_) const {
;     ...
;             for (int j = 0; j < 8; ++j) {
;                 const f32x4 xg = acc[j >> 2][0][j & 3][n] * rsv[j], xv = acc[j >> 2][1][j & 3][n] * rsv[j];
;                 const f32x4 gc = gb + g2 * xg + g1 * pg1 + g0 * pg2, vc = vb + v2 * xv + v1 * pv1 + v0 * pv2;
;                 f32x4 sg;
; #pragma unroll
;                 for (int e = 0; e < 4; ++e) sg[e] = __builtin_amdgcn_rcpf(1.f + __expf(-gc[e]));
;                 const f32x4 o4 = gc * sg * vc;
;                 pg2 = pg1; pg1 = xg; pv2 = pv1; pv1 = xv;
;                 if (rb + j >= 2 && tb + j < T_) { u32x2 w; w.x = cvt_pk_bf16(o4[0], o4[1]); w.y = cvt_pk_bf16(o4[2], o4[3]); *(u32x2*)(act + (size_t)(tb + j) * FF_ + 128 * u.pn + cl + 4 * n) = w; }
.LBB0_957:
	s_or_b64 exec, exec, s[4:5]
	v_mov_b32_e32 v219, v218
	v_mov_b32_e32 v32, v218
	v_mov_b32_e32 v33, v218
	v_pk_mul_f32 v[14:15], v[14:15], v[32:33]
	v_pk_mul_f32 v[12:13], v[12:13], v[218:219]
	v_pk_mul_f32 v[10:11], v[10:11], v[32:33]
	v_pk_mul_f32 v[8:9], v[8:9], v[218:219]
	s_and_saveexec_b64 s[4:5], s[14:15]
	s_cbranch_execz .LBB0_959
	v_pk_fma_f32 v[32:33], v[10:11], v[102:103], v[106:107]
	v_pk_fma_f32 v[34:35], v[8:9], v[100:101], v[104:105]
	v_pk_fma_f32 v[32:33], v[18:19], v[98:99], v[32:33]
	v_pk_fma_f32 v[34:35], v[16:17], v[96:97], v[34:35]
	v_pk_fma_f32 v[26:27], v[26:27], v[82:83], v[32:33]
	v_pk_fma_f32 v[24:25], v[24:25], v[80:81], v[34:35]
	v_pk_fma_f32 v[32:33], v[14:15], v[90:91], v[94:95]
	v_pk_fma_f32 v[34:35], v[12:13], v[88:89], v[92:93]
	v_pk_fma_f32 v[32:33], v[22:23], v[86:87], v[32:33]
	v_pk_fma_f32 v[34:35], v[20:21], v[84:85], v[34:35]
	v_pk_fma_f32 v[30:31], v[30:31], v[78:79], v[32:33]
	v_pk_fma_f32 v[28:29], v[28:29], v[76:77], v[34:35]
	v_mul_f32_e32 v34, 0xbfb8aa3b, v30
	v_mul_f32_e32 v32, 0xbfb8aa3b, v28
	v_mul_f32_e32 v33, 0xbfb8aa3b, v29
	v_mul_f32_e32 v35, 0xbfb8aa3b, v31
	v_exp_f32_e32 v32, v32
	v_exp_f32_e32 v33, v33
	v_exp_f32_e32 v34, v34
	v_exp_f32_e32 v35, v35
	v_add_f32_e32 v32, 1.0, v32
	v_add_f32_e32 v33, 1.0, v33
	v_add_f32_e32 v34, 1.0, v34
	v_add_f32_e32 v35, 1.0, v35
	v_rcp_f32_e32 v32, v32
	v_rcp_f32_e32 v33, v33
	v_rcp_f32_e32 v34, v34
	v_rcp_f32_e32 v35, v35
	v_pk_mul_f32 v[28:29], v[28:29], v[32:33]
	s_nop 0
	v_pk_mul_f32 v[24:25], v[24:25], v[28:29]
	v_pk_mul_f32 v[30:31], v[30:31], v[34:35]
	v_cvt_pk_bf16_f32 v24, v24, v25
	s_nop 0
	v_pk_mul_f32 v[26:27], v[26:27], v[30:31]
	s_nop 0
	v_cvt_pk_bf16_f32 v25, v26, v27
	v_mad_i64_i32 v[26:27], s[6:7], v217, s37, v[50:51]
	global_store_dwordx2 v[26:27], v[24:25], off offset:8
.LBB0_959:
	s_or_b64 exec, exec, s[4:5]
	v_mov_b32_e32 v217, v216
	v_mov_b32_e32 v24, v216
	v_mov_b32_e32 v25, v216
	v_pk_mul_f32 v[6:7], v[6:7], v[24:25]
	v_pk_mul_f32 v[4:5], v[4:5], v[216:217]
	v_pk_mul_f32 v[2:3], v[2:3], v[24:25]
	v_pk_mul_f32 v[0:1], v[0:1], v[216:217]
	s_and_saveexec_b64 s[4:5], s[26:27]
	s_cbranch_execz .LBB0_961
	v_pk_fma_f32 v[24:25], v[2:3], v[102:103], v[106:107]
	v_pk_fma_f32 v[26:27], v[0:1], v[100:101], v[104:105]
	v_pk_fma_f32 v[24:25], v[10:11], v[98:99], v[24:25]
	v_pk_fma_f32 v[26:27], v[8:9], v[96:97], v[26:27]
	v_pk_fma_f32 v[18:19], v[18:19], v[82:83], v[24:25]
	v_pk_fma_f32 v[16:17], v[16:17], v[80:81], v[26:27]
	v_pk_fma_f32 v[24:25], v[6:7], v[90:91], v[94:95]
	v_pk_fma_f32 v[26:27], v[4:5], v[88:89], v[92:93]
	v_pk_fma_f32 v[24:25], v[14:15], v[86:87], v[24:25]
	v_pk_fma_f32 v[26:27], v[12:13], v[84:85], v[26:27]
	v_pk_fma_f32 v[22:23], v[22:23], v[78:79], v[24:25]
	v_pk_fma_f32 v[20:21], v[20:21], v[76:77], v[26:27]
	v_mul_f32_e32 v26, 0xbfb8aa3b, v22
	v_mul_f32_e32 v24, 0xbfb8aa3b, v20
	v_mul_f32_e32 v25, 0xbfb8aa3b, v21
	v_mul_f32_e32 v27, 0xbfb8aa3b, v23
	v_exp_f32_e32 v24, v24
	v_exp_f32_e32 v25, v25
	v_exp_f32_e32 v26, v26
	v_exp_f32_e32 v27, v27
	v_add_f32_e32 v24, 1.0, v24
	v_add_f32_e32 v25, 1.0, v25
	v_add_f32_e32 v26, 1.0, v26
	v_add_f32_e32 v27, 1.0, v27
	v_rcp_f32_e32 v24, v24
	v_rcp_f32_e32 v25, v25
	v_rcp_f32_e32 v26, v26
	v_rcp_f32_e32 v27, v27
	v_pk_mul_f32 v[20:21], v[20:21], v[24:25]
	s_nop 0
	v_pk_mul_f32 v[16:17], v[16:17], v[20:21]
	v_pk_mul_f32 v[22:23], v[22:23], v[26:27]
	v_cvt_pk_bf16_f32 v16, v16, v17
	s_nop 0
	v_pk_mul_f32 v[18:19], v[18:19], v[22:23]
	s_nop 0
	v_cvt_pk_bf16_f32 v17, v18, v19
	v_mad_i64_i32 v[18:19], s[6:7], v246, s37, v[50:51]
	global_store_dwordx2 v[18:19], v[16:17], off offset:8
.LBB0_961:
	s_or_b64 exec, exec, s[4:5]
	s_and_saveexec_b64 s[4:5], s[28:29]
	s_cbranch_execz .LBB0_963
	v_pk_fma_f32 v[16:17], v[110:111], v[102:103], v[106:107]
	v_pk_fma_f32 v[18:19], v[62:63], v[100:101], v[104:105]
	v_pk_fma_f32 v[16:17], v[2:3], v[98:99], v[16:17]
	v_pk_fma_f32 v[18:19], v[0:1], v[96:97], v[18:19]
	v_pk_fma_f32 v[10:11], v[10:11], v[82:83], v[16:17]
	v_pk_fma_f32 v[8:9], v[8:9], v[80:81], v[18:19]
	v_pk_fma_f32 v[16:17], v[64:65], v[90:91], v[94:95]
	v_pk_fma_f32 v[18:19], v[48:49], v[88:89], v[92:93]
	v_pk_fma_f32 v[16:17], v[6:7], v[86:87], v[16:17]
	v_pk_fma_f32 v[18:19], v[4:5], v[84:85], v[18:19]
	v_pk_fma_f32 v[14:15], v[14:15], v[78:79], v[16:17]
	v_pk_fma_f32 v[12:13], v[12:13], v[76:77], v[18:19]
	v_mul_f32_e32 v18, 0xbfb8aa3b, v14
	v_mul_f32_e32 v16, 0xbfb8aa3b, v12
	v_mul_f32_e32 v17, 0xbfb8aa3b, v13
	v_mul_f32_e32 v19, 0xbfb8aa3b, v15
	v_exp_f32_e32 v16, v16
	v_exp_f32_e32 v17, v17
	v_exp_f32_e32 v18, v18
	v_exp_f32_e32 v19, v19
	v_add_f32_e32 v16, 1.0, v16
	v_add_f32_e32 v17, 1.0, v17
	v_add_f32_e32 v18, 1.0, v18
	v_add_f32_e32 v19, 1.0, v19
	v_rcp_f32_e32 v16, v16
	v_rcp_f32_e32 v17, v17
	v_rcp_f32_e32 v18, v18
	v_rcp_f32_e32 v19, v19
	v_pk_mul_f32 v[12:13], v[12:13], v[16:17]
	s_nop 0
	v_pk_mul_f32 v[8:9], v[8:9], v[12:13]
	v_pk_mul_f32 v[14:15], v[14:15], v[18:19]
	v_cvt_pk_bf16_f32 v8, v8, v9
	s_nop 0
	v_pk_mul_f32 v[10:11], v[10:11], v[14:15]
	s_nop 0
	v_cvt_pk_bf16_f32 v9, v10, v11
	v_mad_i64_i32 v[10:11], s[6:7], v245, s37, v[50:51]
	global_store_dwordx2 v[10:11], v[8:9], off offset:8
.LBB0_963:
	s_or_b64 exec, exec, s[4:5]
	s_and_saveexec_b64 s[4:5], s[0:1]
	s_cbranch_execz .LBB0_965
	v_pk_fma_f32 v[12:13], v[52:53], v[88:89], v[92:93]
	v_pk_fma_f32 v[8:9], v[112:113], v[102:103], v[106:107]
	v_pk_fma_f32 v[12:13], v[48:49], v[84:85], v[12:13]
	v_pk_fma_f32 v[10:11], v[66:67], v[100:101], v[104:105]
	v_pk_fma_f32 v[4:5], v[4:5], v[76:77], v[12:13]
	v_pk_fma_f32 v[8:9], v[110:111], v[98:99], v[8:9]
	v_mul_f32_e32 v12, 0xbfb8aa3b, v4
	v_exp_f32_e32 v14, v12
	v_pk_fma_f32 v[12:13], v[108:109], v[90:91], v[94:95]
	v_pk_fma_f32 v[10:11], v[62:63], v[96:97], v[10:11]
	v_pk_fma_f32 v[12:13], v[64:65], v[86:87], v[12:13]
	v_pk_fma_f32 v[2:3], v[2:3], v[82:83], v[8:9]
	v_pk_fma_f32 v[6:7], v[6:7], v[78:79], v[12:13]
	v_add_f32_e32 v12, 1.0, v14
	v_mul_f32_e32 v13, 0xbfb8aa3b, v5
	v_mul_f32_e32 v14, 0xbfb8aa3b, v6
	v_mul_f32_e32 v15, 0xbfb8aa3b, v7
	v_exp_f32_e32 v13, v13
	v_exp_f32_e32 v14, v14
	v_exp_f32_e32 v15, v15
	v_rcp_f32_e32 v12, v12
	v_add_f32_e32 v13, 1.0, v13
	v_add_f32_e32 v14, 1.0, v14
	v_add_f32_e32 v15, 1.0, v15
	v_rcp_f32_e32 v14, v14
	v_rcp_f32_e32 v15, v15
	v_rcp_f32_e32 v13, v13
	v_pk_fma_f32 v[0:1], v[0:1], v[80:81], v[10:11]
	v_pk_mul_f32 v[6:7], v[6:7], v[14:15]
	v_pk_mul_f32 v[4:5], v[4:5], v[12:13]
	v_pk_mul_f32 v[2:3], v[2:3], v[6:7]
	v_pk_mul_f32 v[0:1], v[0:1], v[4:5]
	s_nop 0
	v_cvt_pk_bf16_f32 v0, v0, v1
	v_cvt_pk_bf16_f32 v1, v2, v3
	v_mad_i64_i32 v[2:3], s[0:1], v244, s37, v[50:51]
	global_store_dwordx2 v[2:3], v[0:1], off offset:8
